# v52 plus nop padding after each edited region so every downstream hot loop keeps v50's code alignment (mod 256)
# speedup vs baseline: 1.0009x; 1.0009x over previous
.LBB0_614:
	s_or_b64 exec, exec, s[20:21]
	s_add_u32 s3, s24, s19
	s_addc_u32 s21, s25, 0
	v_mov_b32_e32 v32, v182
	s_add_u32 s20, s3, 0x8801000
	s_waitcnt lgkmcnt(0)
	s_barrier
	s_mov_b64 s[98:99], 0xc0000
	s_addc_u32 s21, s21, 0
	v_and_b32_e32 v34, 63, v32
	s_lshl_b64 s[0:1], s[0:1], 1
	s_add_u32 s0, s63, s0
	v_ashrrev_i32_e32 v32, 1, v34
	s_addc_u32 s1, s64, s1
	v_and_b32_e32 v32, -8, v32
	s_add_u32 s0, s0, s19
	v_add_u32_e32 v32, s80, v32
	s_addc_u32 s1, s1, 0
	s_lshl_b32 s2, s2, 2
	v_ashrrev_i32_e32 v33, 31, v32
	v_and_or_b32 v174, v34, 15, s79
	v_mov_b64_e32 v[172:173], s[20:21]
	s_add_u32 s2, s46, s2
	v_mad_i64_i32 v[34:35], s[20:21], v174, s77, v[172:173]
	v_lshlrev_b64 v[86:87], 1, v[32:33]
	s_addc_u32 s3, s47, 0
	v_lshl_add_u64 v[34:35], v[34:35], 0, v[86:87]
	v_lshl_add_u64 v[236:237], v[34:35], 0, s[98:99]
	global_load_dwordx4 v[186:189], v[34:35], off nt
	v_lshl_add_u64 v[32:33], v[32:33], 2, s[2:3]
	global_load_dwordx4 v[44:47], v[32:33], off
	global_load_dwordx4 v[36:39], v[32:33], off offset:16
	v_or_b32_e32 v180, 16, v174
	v_or_b32_e32 v178, 32, v174
	v_mad_i64_i32 v[40:41], s[2:3], v180, s77, v[172:173]
	v_mad_i64_i32 v[42:43], s[2:3], v178, s77, v[172:173]
	v_lshl_add_u32 v152, v174, 2, 0
	v_lshl_add_u64 v[40:41], v[40:41], 0, v[86:87]
	v_lshl_add_u64 v[42:43], v[42:43], 0, v[86:87]
	global_load_dwordx4 v[190:193], v[34:35], off offset:256 nt
	v_lshl_add_u64 v[238:239], v[40:41], 0, s[98:99]
	global_load_dwordx4 v[68:71], v[40:41], off nt
	global_load_dwordx4 v[64:67], v[40:41], off offset:256 nt
	v_lshl_add_u64 v[240:241], v[42:43], 0, s[98:99]
	global_load_dwordx4 v[60:63], v[42:43], off nt
	global_load_dwordx4 v[56:59], v[42:43], off offset:256 nt
	ds_read_b32 v35, v152
	ds_read_b32 v41, v152 offset:1024
	ds_read_b32 v43, v152 offset:2048
	ds_read_b32 v197, v152 offset:3072
	ds_read_b32 v34, v152 offset:4096
	ds_read_b32 v40, v152 offset:5120
	ds_read_b32 v42, v152 offset:6144
	ds_read_b32 v196, v152 offset:7168
	v_or_b32_e32 v176, 48, v174
	v_ashrrev_i32_e32 v175, 31, v174
	s_waitcnt lgkmcnt(0)
	v_pk_add_f32 v[34:35], v[34:35], v[40:41]
	v_mad_i64_i32 v[48:49], s[2:3], v176, s77, v[172:173]
	v_pk_add_f32 v[34:35], v[34:35], v[42:43]
	v_lshlrev_b64 v[50:51], 11, v[174:175]
	v_pk_add_f32 v[34:35], v[34:35], v[196:197]
	v_lshl_add_u64 v[48:49], v[48:49], 0, v[86:87]
	v_pk_mul_f32 v[196:197], v[34:35], s[16:17] op_sel_hi:[1,0]
	v_lshl_add_u64 v[194:195], s[0:1], 0, v[50:51]
	v_fma_f32 v34, -v197, v197, v196
	v_max_f32_e32 v34, 0, v34
	v_add_f32_e32 v34, 0x358637bd, v34
	v_mul_f32_e32 v35, 0x4b800000, v34
	v_cmp_gt_f32_e32 vcc, s78, v34
	v_lshl_add_u64 v[242:243], v[48:49], 0, s[98:99]
	global_load_dwordx4 v[52:55], v[48:49], off nt
	s_nop 0
	global_load_dwordx4 v[48:51], v[48:49], off offset:256 nt
	v_cndmask_b32_e32 v34, v34, v35, vcc
	v_rsq_f32_e32 v175, v34
	global_load_dwordx4 v[40:43], v[32:33], off offset:512
	s_nop 0
	global_load_dwordx4 v[32:35], v[32:33], off offset:528
	global_load_dwordx4 v[204:207], v[236:237], off nt
	global_load_dwordx4 v[208:211], v[236:237], off offset:256 nt
	global_load_dwordx4 v[212:215], v[238:239], off nt
	global_load_dwordx4 v[216:219], v[238:239], off offset:256 nt
	global_load_dwordx4 v[220:223], v[240:241], off nt
	global_load_dwordx4 v[224:227], v[240:241], off offset:256 nt
	global_load_dwordx4 v[228:231], v[242:243], off nt
	global_load_dwordx4 v[232:235], v[242:243], off offset:256 nt
	v_pk_add_f32 v[28:29], v[28:29], v[196:197] op_sel:[0,1] neg_lo:[0,1] neg_hi:[0,1]
	v_pk_add_f32 v[30:31], v[30:31], v[196:197] op_sel:[0,1] neg_lo:[0,1] neg_hi:[0,1]
	v_mul_f32_e32 v177, 0x45800000, v175
	v_cndmask_b32_e32 v198, v175, v177, vcc
	v_pk_mul_f32 v[28:29], v[28:29], v[198:199] op_sel_hi:[1,0]
	v_pk_mul_f32 v[30:31], v[30:31], v[198:199] op_sel_hi:[1,0]
	v_pk_add_f32 v[166:167], v[166:167], v[196:197] op_sel:[0,1] neg_lo:[0,1] neg_hi:[0,1]
	v_pk_add_f32 v[150:151], v[150:151], v[196:197] op_sel:[0,1] neg_lo:[0,1] neg_hi:[0,1]
	v_pk_mul_f32 v[166:167], v[166:167], v[198:199] op_sel_hi:[1,0]
	v_pk_mul_f32 v[150:151], v[150:151], v[198:199] op_sel_hi:[1,0]
	v_pk_add_f32 v[164:165], v[164:165], v[196:197] op_sel:[0,1] neg_lo:[0,1] neg_hi:[0,1]
	v_pk_add_f32 v[148:149], v[148:149], v[196:197] op_sel:[0,1] neg_lo:[0,1] neg_hi:[0,1]
	v_pk_mul_f32 v[164:165], v[164:165], v[198:199] op_sel_hi:[1,0]
	v_pk_mul_f32 v[148:149], v[148:149], v[198:199] op_sel_hi:[1,0]
	v_pk_add_f32 v[140:141], v[140:141], v[196:197] op_sel:[0,1] neg_lo:[0,1] neg_hi:[0,1]
	v_ashrrev_i32_e32 v181, 31, v180
	v_pk_mul_f32 v[140:141], v[140:141], v[198:199] op_sel_hi:[1,0]
	s_add_i32 s18, s18, s96
	s_add_i32 s69, s69, s70
	s_add_i32 s71, s71, s72
	s_cmpk_gt_i32 s18, 0xff
	s_waitcnt vmcnt(8)
	v_lshlrev_b32_e32 v200, 16, v186
	v_and_b32_e32 v201, 0xffff0000, v186
	v_mul_f32_e32 v175, 0xbfb8aa3b, v200
	v_mul_f32_e32 v177, 0xbfb8aa3b, v201
	v_exp_f32_e32 v175, v175
	v_exp_f32_e32 v177, v177
	v_lshlrev_b32_e32 v186, 16, v187
	v_and_b32_e32 v187, 0xffff0000, v187
	v_add_f32_e32 v175, 1.0, v175
	v_mul_f32_e32 v179, 0xbfb8aa3b, v186
	v_add_f32_e32 v177, 1.0, v177
	v_rcp_f32_e32 v202, v175
	v_mul_f32_e32 v175, 0xbfb8aa3b, v187
	v_rcp_f32_e32 v203, v177
	v_exp_f32_e32 v177, v179
	v_exp_f32_e32 v175, v175
	v_pk_mul_f32 v[28:29], v[44:45], v[28:29]
	v_pk_mul_f32 v[200:201], v[202:203], v[200:201]
	v_add_f32_e32 v177, 1.0, v177
	v_add_f32_e32 v175, 1.0, v175
	v_pk_mul_f32 v[28:29], v[200:201], v[28:29]
	v_rcp_f32_e32 v200, v177
	v_rcp_f32_e32 v201, v175
	v_pk_mul_f32 v[30:31], v[46:47], v[30:31]
	v_pk_mul_f32 v[166:167], v[36:37], v[166:167]
	v_cvt_pk_bf16_f32 v28, v28, v29
	v_pk_mul_f32 v[186:187], v[200:201], v[186:187]
	v_lshlrev_b32_e32 v200, 16, v188
	v_and_b32_e32 v201, 0xffff0000, v188
	v_mul_f32_e32 v175, 0xbfb8aa3b, v200
	v_exp_f32_e32 v175, v175
	v_mul_f32_e32 v177, 0xbfb8aa3b, v201
	v_exp_f32_e32 v177, v177
	v_pk_mul_f32 v[30:31], v[186:187], v[30:31]
	v_add_f32_e32 v175, 1.0, v175
	v_rcp_f32_e32 v186, v175
	v_add_f32_e32 v175, 1.0, v177
	v_lshlrev_b32_e32 v188, 16, v189
	v_rcp_f32_e32 v187, v175
	v_and_b32_e32 v189, 0xffff0000, v189
	v_mul_f32_e32 v175, 0xbfb8aa3b, v188
	v_exp_f32_e32 v175, v175
	v_mul_f32_e32 v177, 0xbfb8aa3b, v189
	v_exp_f32_e32 v177, v177
	v_pk_mul_f32 v[186:187], v[186:187], v[200:201]
	v_add_f32_e32 v175, 1.0, v175
	v_pk_mul_f32 v[166:167], v[186:187], v[166:167]
	v_rcp_f32_e32 v186, v175
	v_add_f32_e32 v175, 1.0, v177
	v_rcp_f32_e32 v187, v175
	v_cvt_pk_bf16_f32 v29, v30, v31
	v_cvt_pk_bf16_f32 v30, v166, v167
	v_lshlrev_b32_e32 v166, 16, v190
	v_and_b32_e32 v167, 0xffff0000, v190
	v_mul_f32_e32 v175, 0xbfb8aa3b, v166
	v_mul_f32_e32 v177, 0xbfb8aa3b, v167
	v_exp_f32_e32 v175, v175
	v_exp_f32_e32 v177, v177
	v_pk_mul_f32 v[150:151], v[38:39], v[150:151]
	v_pk_mul_f32 v[186:187], v[186:187], v[188:189]
	s_waitcnt lgkmcnt(0)
	v_pk_mul_f32 v[164:165], v[42:43], v[164:165]
	v_pk_mul_f32 v[150:151], v[186:187], v[150:151]
	v_pk_mul_f32 v[148:149], v[32:33], v[148:149]
	v_cvt_pk_bf16_f32 v31, v150, v151
	v_lshl_add_u64 v[150:151], v[194:195], 0, v[86:87]
	global_store_dwordx4 v[150:151], v[28:31], off
	v_pk_mul_f32 v[140:141], v[34:35], v[140:141]
	v_ashrrev_i32_e32 v179, 31, v178
	v_add_f32_e32 v28, 1.0, v175
	v_add_f32_e32 v29, 1.0, v177
	v_rcp_f32_e32 v28, v28
	v_rcp_f32_e32 v29, v29
	v_pk_add_f32 v[30:31], v[170:171], v[196:197] op_sel:[0,1] neg_lo:[0,1] neg_hi:[0,1]
	v_ashrrev_i32_e32 v177, 31, v176
	v_pk_mul_f32 v[30:31], v[30:31], v[198:199] op_sel_hi:[1,0]
	v_pk_mul_f32 v[28:29], v[28:29], v[166:167]
	v_lshlrev_b32_e32 v166, 16, v191
	v_and_b32_e32 v167, 0xffff0000, v191
	v_mul_f32_e32 v170, 0xbfb8aa3b, v166
	v_mul_f32_e32 v171, 0xbfb8aa3b, v167
	v_exp_f32_e32 v170, v170
	v_exp_f32_e32 v171, v171
	v_pk_mul_f32 v[30:31], v[40:41], v[30:31]
	s_nop 0
	v_pk_mul_f32 v[28:29], v[28:29], v[30:31]
	v_add_f32_e32 v30, 1.0, v170
	v_add_f32_e32 v31, 1.0, v171
	v_rcp_f32_e32 v30, v30
	v_rcp_f32_e32 v31, v31
	v_cvt_pk_bf16_f32 v28, v28, v29
	v_pk_mul_f32 v[30:31], v[30:31], v[166:167]
	v_lshlrev_b32_e32 v166, 16, v192
	v_and_b32_e32 v167, 0xffff0000, v192
	v_mul_f32_e32 v170, 0xbfb8aa3b, v166
	v_mul_f32_e32 v171, 0xbfb8aa3b, v167
	v_exp_f32_e32 v170, v170
	v_exp_f32_e32 v171, v171
	v_pk_mul_f32 v[30:31], v[30:31], v[164:165]
	v_add_f32_e32 v164, 1.0, v170
	v_add_f32_e32 v165, 1.0, v171
	v_rcp_f32_e32 v164, v164
	v_rcp_f32_e32 v165, v165
	v_cvt_pk_bf16_f32 v29, v30, v31
	v_pk_mul_f32 v[164:165], v[164:165], v[166:167]
	v_lshlrev_b32_e32 v166, 16, v193
	v_and_b32_e32 v167, 0xffff0000, v193
	v_mul_f32_e32 v170, 0xbfb8aa3b, v166
	v_mul_f32_e32 v171, 0xbfb8aa3b, v167
	v_exp_f32_e32 v170, v170
	v_exp_f32_e32 v171, v171
	v_pk_mul_f32 v[148:149], v[164:165], v[148:149]
	v_add_f32_e32 v164, 1.0, v170
	v_add_f32_e32 v165, 1.0, v171
	v_rcp_f32_e32 v164, v164
	v_rcp_f32_e32 v165, v165
	v_cvt_pk_bf16_f32 v30, v148, v149
	v_pk_mul_f32 v[164:165], v[164:165], v[166:167]
	s_nop 0
	v_pk_mul_f32 v[140:141], v[164:165], v[140:141]
	s_nop 0
	v_cvt_pk_bf16_f32 v31, v140, v141
	global_store_dwordx4 v[150:151], v[28:31], off offset:256
	ds_read_b32 v29, v152 offset:64
	ds_read_b32 v31, v152 offset:1088
	ds_read_b32 v141, v152 offset:2112
	ds_read_b32 v149, v152 offset:3136
	ds_read_b32 v28, v152 offset:4160
	ds_read_b32 v30, v152 offset:5184
	ds_read_b32 v140, v152 offset:6208
	ds_read_b32 v148, v152 offset:7232
	s_waitcnt lgkmcnt(0)
	v_pk_add_f32 v[28:29], v[28:29], v[30:31]
	s_nop 0
	v_pk_add_f32 v[28:29], v[28:29], v[140:141]
	v_lshlrev_b64 v[140:141], 11, v[180:181]
	v_pk_add_f32 v[28:29], v[28:29], v[148:149]
	v_lshlrev_b32_e32 v148, 16, v68
	v_pk_mul_f32 v[28:29], v[28:29], s[16:17] op_sel_hi:[1,0]
	v_and_b32_e32 v149, 0xffff0000, v68
	v_fma_f32 v30, -v29, v29, v28
	v_max_f32_e32 v30, 0, v30
	v_add_f32_e32 v30, 0x358637bd, v30
	v_mul_f32_e32 v31, 0x4b800000, v30
	v_cmp_gt_f32_e32 vcc, s78, v30
	v_mul_f32_e32 v68, 0xbfb8aa3b, v149
	v_exp_f32_e32 v68, v68
	v_cndmask_b32_e32 v30, v30, v31, vcc
	v_rsq_f32_e32 v30, v30
	v_pk_add_f32 v[20:21], v[20:21], v[28:29] op_sel:[0,1] neg_lo:[0,1] neg_hi:[0,1]
	v_pk_add_f32 v[22:23], v[22:23], v[28:29] op_sel:[0,1] neg_lo:[0,1] neg_hi:[0,1]
	v_pk_add_f32 v[136:137], v[136:137], v[28:29] op_sel:[0,1] neg_lo:[0,1] neg_hi:[0,1]
	v_mul_f32_e32 v31, 0x45800000, v30
	v_cndmask_b32_e32 v30, v30, v31, vcc
	v_mul_f32_e32 v31, 0xbfb8aa3b, v148
	v_exp_f32_e32 v31, v31
	v_lshl_add_u64 v[140:141], s[0:1], 0, v[140:141]
	v_pk_add_f32 v[130:131], v[130:131], v[28:29] op_sel:[0,1] neg_lo:[0,1] neg_hi:[0,1]
	v_add_f32_e32 v31, 1.0, v31
	v_rcp_f32_e32 v150, v31
	v_add_f32_e32 v31, 1.0, v68
	v_rcp_f32_e32 v151, v31
	v_lshlrev_b32_e32 v68, 16, v69
	v_pk_mul_f32 v[20:21], v[20:21], v[30:31] op_sel_hi:[1,0]
	v_and_b32_e32 v69, 0xffff0000, v69
	v_mul_f32_e32 v31, 0xbfb8aa3b, v68
	v_pk_mul_f32 v[148:149], v[150:151], v[148:149]
	v_exp_f32_e32 v31, v31
	v_mul_f32_e32 v150, 0xbfb8aa3b, v69
	v_exp_f32_e32 v150, v150
	v_pk_mul_f32 v[20:21], v[44:45], v[20:21]
	v_add_f32_e32 v31, 1.0, v31
	v_pk_mul_f32 v[20:21], v[148:149], v[20:21]
	v_rcp_f32_e32 v148, v31
	v_add_f32_e32 v31, 1.0, v150
	v_rcp_f32_e32 v149, v31
	v_pk_mul_f32 v[22:23], v[22:23], v[30:31] op_sel_hi:[1,0]
	v_pk_add_f32 v[150:151], v[154:155], v[28:29] op_sel:[0,1] neg_lo:[0,1] neg_hi:[0,1]
	v_pk_mul_f32 v[22:23], v[46:47], v[22:23]
	v_pk_mul_f32 v[68:69], v[148:149], v[68:69]
	v_lshlrev_b32_e32 v148, 16, v70
	v_and_b32_e32 v149, 0xffff0000, v70
	v_mul_f32_e32 v31, 0xbfb8aa3b, v148
	v_exp_f32_e32 v31, v31
	v_mul_f32_e32 v70, 0xbfb8aa3b, v149
	v_exp_f32_e32 v70, v70
	v_pk_mul_f32 v[22:23], v[68:69], v[22:23]
	v_add_f32_e32 v31, 1.0, v31
	v_rcp_f32_e32 v68, v31
	v_add_f32_e32 v31, 1.0, v70
	v_rcp_f32_e32 v69, v31
	v_lshlrev_b32_e32 v70, 16, v71
	v_pk_mul_f32 v[150:151], v[150:151], v[30:31] op_sel_hi:[1,0]
	v_and_b32_e32 v71, 0xffff0000, v71
	v_mul_f32_e32 v31, 0xbfb8aa3b, v70
	v_pk_mul_f32 v[68:69], v[68:69], v[148:149]
	v_exp_f32_e32 v31, v31
	v_mul_f32_e32 v148, 0xbfb8aa3b, v71
	v_exp_f32_e32 v149, v148
	v_cvt_pk_bf16_f32 v20, v20, v21
	v_add_f32_e32 v31, 1.0, v31
	v_rcp_f32_e32 v148, v31
	v_add_f32_e32 v31, 1.0, v149
	v_rcp_f32_e32 v149, v31
	v_pk_mul_f32 v[136:137], v[136:137], v[30:31] op_sel_hi:[1,0]
	v_cvt_pk_bf16_f32 v21, v22, v23
	v_pk_mul_f32 v[136:137], v[38:39], v[136:137]
	v_pk_mul_f32 v[70:71], v[148:149], v[70:71]
	v_pk_mul_f32 v[150:151], v[36:37], v[150:151]
	v_pk_mul_f32 v[70:71], v[70:71], v[136:137]
	v_pk_mul_f32 v[68:69], v[68:69], v[150:151]
	v_cvt_pk_bf16_f32 v23, v70, v71
	v_lshlrev_b32_e32 v70, 16, v64
	v_and_b32_e32 v71, 0xffff0000, v64
	v_mul_f32_e32 v31, 0xbfb8aa3b, v70
	v_mul_f32_e32 v64, 0xbfb8aa3b, v71
	v_exp_f32_e32 v31, v31
	v_exp_f32_e32 v64, v64
	v_cvt_pk_bf16_f32 v22, v68, v69
	v_lshl_add_u64 v[68:69], v[140:141], 0, v[86:87]
	global_store_dwordx4 v[68:69], v[20:23], off
	s_nop 1
	v_add_f32_e32 v20, 1.0, v31
	v_add_f32_e32 v21, 1.0, v64
	v_rcp_f32_e32 v20, v20
	v_rcp_f32_e32 v21, v21
	v_pk_add_f32 v[22:23], v[168:169], v[28:29] op_sel:[0,1] neg_lo:[0,1] neg_hi:[0,1]
	v_lshlrev_b32_e32 v64, 16, v65
	v_and_b32_e32 v65, 0xffff0000, v65
	v_pk_mul_f32 v[22:23], v[22:23], v[30:31] op_sel_hi:[1,0]
	v_pk_mul_f32 v[20:21], v[20:21], v[70:71]
	v_mul_f32_e32 v31, 0xbfb8aa3b, v64
	v_mul_f32_e32 v70, 0xbfb8aa3b, v65
	v_exp_f32_e32 v31, v31
	v_exp_f32_e32 v70, v70
	v_pk_mul_f32 v[22:23], v[40:41], v[22:23]
	s_nop 0
	v_pk_mul_f32 v[20:21], v[20:21], v[22:23]
	v_add_f32_e32 v22, 1.0, v31
	v_add_f32_e32 v23, 1.0, v70
	v_rcp_f32_e32 v22, v22
	v_rcp_f32_e32 v23, v23
	v_pk_add_f32 v[70:71], v[156:157], v[28:29] op_sel:[0,1] neg_lo:[0,1] neg_hi:[0,1]
	v_pk_add_f32 v[28:29], v[120:121], v[28:29] op_sel:[0,1] neg_lo:[0,1] neg_hi:[0,1]
	v_pk_mul_f32 v[70:71], v[70:71], v[30:31] op_sel_hi:[1,0]
	v_pk_mul_f32 v[22:23], v[22:23], v[64:65]
	v_lshlrev_b32_e32 v64, 16, v66
	v_and_b32_e32 v65, 0xffff0000, v66
	v_mul_f32_e32 v31, 0xbfb8aa3b, v64
	v_exp_f32_e32 v31, v31
	v_mul_f32_e32 v66, 0xbfb8aa3b, v65
	v_exp_f32_e32 v66, v66
	v_pk_mul_f32 v[70:71], v[42:43], v[70:71]
	v_add_f32_e32 v31, 1.0, v31
	v_pk_mul_f32 v[22:23], v[22:23], v[70:71]
	v_rcp_f32_e32 v70, v31
	v_add_f32_e32 v31, 1.0, v66
	v_rcp_f32_e32 v71, v31
	v_lshlrev_b32_e32 v66, 16, v67
	v_pk_mul_f32 v[130:131], v[130:131], v[30:31] op_sel_hi:[1,0]
	v_and_b32_e32 v67, 0xffff0000, v67
	v_mul_f32_e32 v31, 0xbfb8aa3b, v66
	v_pk_mul_f32 v[64:65], v[70:71], v[64:65]
	v_exp_f32_e32 v31, v31
	v_mul_f32_e32 v70, 0xbfb8aa3b, v67
	v_exp_f32_e32 v71, v70
	v_pk_mul_f32 v[130:131], v[32:33], v[130:131]
	v_add_f32_e32 v31, 1.0, v31
	v_rcp_f32_e32 v70, v31
	v_add_f32_e32 v31, 1.0, v71
	v_rcp_f32_e32 v71, v31
	v_pk_mul_f32 v[28:29], v[28:29], v[30:31] op_sel_hi:[1,0]
	v_pk_mul_f32 v[64:65], v[64:65], v[130:131]
	v_pk_mul_f32 v[28:29], v[34:35], v[28:29]
	v_pk_mul_f32 v[30:31], v[70:71], v[66:67]
	v_cvt_pk_bf16_f32 v20, v20, v21
	v_pk_mul_f32 v[28:29], v[30:31], v[28:29]
	v_cvt_pk_bf16_f32 v21, v22, v23
	v_cvt_pk_bf16_f32 v22, v64, v65
	v_cvt_pk_bf16_f32 v23, v28, v29
	global_store_dwordx4 v[68:69], v[20:23], off offset:256
	ds_read_b32 v21, v152 offset:128
	ds_read_b32 v23, v152 offset:1152
	ds_read_b32 v29, v152 offset:2176
	ds_read_b32 v31, v152 offset:3200
	ds_read_b32 v20, v152 offset:4224
	ds_read_b32 v22, v152 offset:5248
	ds_read_b32 v28, v152 offset:6272
	ds_read_b32 v30, v152 offset:7296
	v_add_u32_e32 v70, 0x80, v174
	v_ashrrev_i32_e32 v71, 31, v70
	s_waitcnt lgkmcnt(0)
	v_pk_add_f32 v[20:21], v[20:21], v[22:23]
	s_nop 0
	v_pk_add_f32 v[20:21], v[20:21], v[28:29]
	v_lshlrev_b64 v[28:29], 11, v[178:179]
	v_pk_add_f32 v[20:21], v[20:21], v[30:31]
	v_lshlrev_b32_e32 v30, 16, v60
	v_pk_mul_f32 v[20:21], v[20:21], s[16:17] op_sel_hi:[1,0]
	v_and_b32_e32 v31, 0xffff0000, v60
	v_fma_f32 v22, -v21, v21, v20
	v_max_f32_e32 v22, 0, v22
	v_add_f32_e32 v22, 0x358637bd, v22
	v_mul_f32_e32 v23, 0x4b800000, v22
	v_cmp_gt_f32_e32 vcc, s78, v22
	v_mul_f32_e32 v60, 0xbfb8aa3b, v31
	v_exp_f32_e32 v60, v60
	v_cndmask_b32_e32 v22, v22, v23, vcc
	v_rsq_f32_e32 v22, v22
	v_pk_add_f32 v[16:17], v[16:17], v[20:21] op_sel:[0,1] neg_lo:[0,1] neg_hi:[0,1]
	v_pk_add_f32 v[18:19], v[18:19], v[20:21] op_sel:[0,1] neg_lo:[0,1] neg_hi:[0,1]
	v_lshl_add_u64 v[28:29], s[0:1], 0, v[28:29]
	v_mul_f32_e32 v23, 0x45800000, v22
	v_cndmask_b32_e32 v22, v22, v23, vcc
	v_mul_f32_e32 v23, 0xbfb8aa3b, v30
	v_exp_f32_e32 v23, v23
	v_lshl_add_u64 v[28:29], v[28:29], 0, v[86:87]
	v_add_f32_e32 v23, 1.0, v23
	v_rcp_f32_e32 v64, v23
	v_add_f32_e32 v23, 1.0, v60
	v_rcp_f32_e32 v65, v23
	v_lshlrev_b32_e32 v60, 16, v61
	v_pk_mul_f32 v[16:17], v[16:17], v[22:23] op_sel_hi:[1,0]
	v_and_b32_e32 v61, 0xffff0000, v61
	v_mul_f32_e32 v23, 0xbfb8aa3b, v60
	v_pk_mul_f32 v[30:31], v[64:65], v[30:31]
	v_exp_f32_e32 v23, v23
	v_mul_f32_e32 v64, 0xbfb8aa3b, v61
	v_exp_f32_e32 v64, v64
	v_pk_mul_f32 v[16:17], v[44:45], v[16:17]
	v_add_f32_e32 v23, 1.0, v23
	v_pk_mul_f32 v[16:17], v[30:31], v[16:17]
	v_rcp_f32_e32 v30, v23
	v_add_f32_e32 v23, 1.0, v64
	v_rcp_f32_e32 v31, v23
	v_pk_mul_f32 v[18:19], v[18:19], v[22:23] op_sel_hi:[1,0]
	v_pk_add_f32 v[64:65], v[134:135], v[20:21] op_sel:[0,1] neg_lo:[0,1] neg_hi:[0,1]
	v_pk_mul_f32 v[18:19], v[46:47], v[18:19]
	v_pk_mul_f32 v[30:31], v[30:31], v[60:61]
	v_lshlrev_b32_e32 v60, 16, v62
	v_and_b32_e32 v61, 0xffff0000, v62
	v_mul_f32_e32 v23, 0xbfb8aa3b, v60
	v_exp_f32_e32 v23, v23
	v_mul_f32_e32 v62, 0xbfb8aa3b, v61
	v_exp_f32_e32 v62, v62
	v_pk_mul_f32 v[18:19], v[30:31], v[18:19]
	v_add_f32_e32 v23, 1.0, v23
	v_rcp_f32_e32 v30, v23
	v_add_f32_e32 v23, 1.0, v62
	v_rcp_f32_e32 v31, v23
	v_pk_mul_f32 v[64:65], v[64:65], v[22:23] op_sel_hi:[1,0]
	v_cvt_pk_bf16_f32 v16, v16, v17
	v_pk_mul_f32 v[64:65], v[36:37], v[64:65]
	v_pk_mul_f32 v[30:31], v[30:31], v[60:61]
	v_lshlrev_b32_e32 v60, 16, v63
	v_and_b32_e32 v61, 0xffff0000, v63
	v_mul_f32_e32 v23, 0xbfb8aa3b, v60
	v_exp_f32_e32 v23, v23
	v_mul_f32_e32 v62, 0xbfb8aa3b, v61
	v_exp_f32_e32 v63, v62
	v_pk_mul_f32 v[30:31], v[30:31], v[64:65]
	v_add_f32_e32 v23, 1.0, v23
	v_rcp_f32_e32 v62, v23
	v_add_f32_e32 v23, 1.0, v63
	v_rcp_f32_e32 v63, v23
	v_pk_add_f32 v[64:65], v[116:117], v[20:21] op_sel:[0,1] neg_lo:[0,1] neg_hi:[0,1]
	v_cvt_pk_bf16_f32 v17, v18, v19
	v_cvt_pk_bf16_f32 v18, v30, v31
	v_lshlrev_b32_e32 v30, 16, v56
	v_and_b32_e32 v31, 0xffff0000, v56
	v_pk_mul_f32 v[64:65], v[64:65], v[22:23] op_sel_hi:[1,0]
	v_mul_f32_e32 v23, 0xbfb8aa3b, v30
	v_mul_f32_e32 v56, 0xbfb8aa3b, v31
	v_exp_f32_e32 v23, v23
	v_exp_f32_e32 v56, v56
	v_pk_mul_f32 v[64:65], v[38:39], v[64:65]
	v_pk_mul_f32 v[60:61], v[62:63], v[60:61]
	s_nop 0
	v_pk_mul_f32 v[60:61], v[60:61], v[64:65]
	s_nop 0
	v_cvt_pk_bf16_f32 v19, v60, v61
	global_store_dwordx4 v[28:29], v[16:19], off
	v_pk_add_f32 v[60:61], v[114:115], v[20:21] op_sel:[0,1] neg_lo:[0,1] neg_hi:[0,1]
	s_nop 0
	v_add_f32_e32 v16, 1.0, v23
	v_add_f32_e32 v17, 1.0, v56
	v_rcp_f32_e32 v16, v16
	v_rcp_f32_e32 v17, v17
	v_pk_add_f32 v[18:19], v[160:161], v[20:21] op_sel:[0,1] neg_lo:[0,1] neg_hi:[0,1]
	v_pk_mul_f32 v[16:17], v[16:17], v[30:31]
	v_lshlrev_b32_e32 v30, 16, v57
	v_and_b32_e32 v31, 0xffff0000, v57
	v_pk_mul_f32 v[18:19], v[18:19], v[22:23] op_sel_hi:[1,0]
	v_mul_f32_e32 v23, 0xbfb8aa3b, v30
	v_mul_f32_e32 v56, 0xbfb8aa3b, v31
	v_exp_f32_e32 v23, v23
	v_exp_f32_e32 v56, v56
	v_pk_mul_f32 v[18:19], v[40:41], v[18:19]
	s_nop 0
	v_pk_mul_f32 v[16:17], v[16:17], v[18:19]
	v_add_f32_e32 v18, 1.0, v23
	v_add_f32_e32 v19, 1.0, v56
	v_rcp_f32_e32 v18, v18
	v_rcp_f32_e32 v19, v19
	v_pk_add_f32 v[56:57], v[138:139], v[20:21] op_sel:[0,1] neg_lo:[0,1] neg_hi:[0,1]
	v_pk_add_f32 v[20:21], v[106:107], v[20:21] op_sel:[0,1] neg_lo:[0,1] neg_hi:[0,1]
	v_pk_mul_f32 v[56:57], v[56:57], v[22:23] op_sel_hi:[1,0]
	v_pk_mul_f32 v[18:19], v[18:19], v[30:31]
	v_lshlrev_b32_e32 v30, 16, v58
	v_and_b32_e32 v31, 0xffff0000, v58
	v_mul_f32_e32 v23, 0xbfb8aa3b, v30
	v_exp_f32_e32 v23, v23
	v_mul_f32_e32 v58, 0xbfb8aa3b, v31
	v_exp_f32_e32 v58, v58
	v_pk_mul_f32 v[56:57], v[42:43], v[56:57]
	v_add_f32_e32 v23, 1.0, v23
	v_pk_mul_f32 v[18:19], v[18:19], v[56:57]
	v_rcp_f32_e32 v56, v23
	v_add_f32_e32 v23, 1.0, v58
	v_rcp_f32_e32 v57, v23
	v_pk_mul_f32 v[60:61], v[60:61], v[22:23] op_sel_hi:[1,0]
	v_cvt_pk_bf16_f32 v16, v16, v17
	v_pk_mul_f32 v[60:61], v[32:33], v[60:61]
	v_pk_mul_f32 v[30:31], v[56:57], v[30:31]
	v_lshlrev_b32_e32 v56, 16, v59
	v_and_b32_e32 v57, 0xffff0000, v59
	v_mul_f32_e32 v23, 0xbfb8aa3b, v56
	v_exp_f32_e32 v23, v23
	v_mul_f32_e32 v58, 0xbfb8aa3b, v57
	v_exp_f32_e32 v59, v58
	v_pk_mul_f32 v[30:31], v[30:31], v[60:61]
	v_add_f32_e32 v23, 1.0, v23
	v_rcp_f32_e32 v58, v23
	v_add_f32_e32 v23, 1.0, v59
	v_rcp_f32_e32 v59, v23
	v_pk_mul_f32 v[20:21], v[20:21], v[22:23] op_sel_hi:[1,0]
	v_cvt_pk_bf16_f32 v17, v18, v19
	v_pk_mul_f32 v[20:21], v[34:35], v[20:21]
	v_pk_mul_f32 v[22:23], v[58:59], v[56:57]
	v_cvt_pk_bf16_f32 v18, v30, v31
	v_pk_mul_f32 v[20:21], v[22:23], v[20:21]
	v_add_u32_e32 v60, 0x90, v174
	v_cvt_pk_bf16_f32 v19, v20, v21
	global_store_dwordx4 v[28:29], v[16:19], off offset:256
	ds_read_b32 v17, v152 offset:192
	ds_read_b32 v19, v152 offset:1216
	ds_read_b32 v21, v152 offset:2240
	ds_read_b32 v23, v152 offset:3264
	ds_read_b32 v16, v152 offset:4288
	ds_read_b32 v18, v152 offset:5312
	ds_read_b32 v20, v152 offset:6336
	ds_read_b32 v22, v152 offset:7360
	v_add_u32_e32 v58, 0xa0, v174
	v_add_u32_e32 v56, 0xb0, v174
	s_waitcnt lgkmcnt(0)
	v_pk_add_f32 v[16:17], v[16:17], v[18:19]
	v_ashrrev_i32_e32 v61, 31, v60
	v_pk_add_f32 v[16:17], v[16:17], v[20:21]
	v_lshlrev_b64 v[20:21], 11, v[176:177]
	v_pk_add_f32 v[16:17], v[16:17], v[22:23]
	v_lshlrev_b32_e32 v22, 16, v52
	v_pk_mul_f32 v[16:17], v[16:17], s[16:17] op_sel_hi:[1,0]
	v_and_b32_e32 v23, 0xffff0000, v52
	v_fma_f32 v18, -v17, v17, v16
	v_max_f32_e32 v18, 0, v18
	v_add_f32_e32 v18, 0x358637bd, v18
	v_mul_f32_e32 v19, 0x4b800000, v18
	v_cmp_gt_f32_e32 vcc, s78, v18
	v_mul_f32_e32 v28, 0xbfb8aa3b, v23
	v_exp_f32_e32 v29, v28
	v_cndmask_b32_e32 v18, v18, v19, vcc
	v_rsq_f32_e32 v18, v18
	v_pk_add_f32 v[8:9], v[8:9], v[16:17] op_sel:[0,1] neg_lo:[0,1] neg_hi:[0,1]
	v_pk_add_f32 v[10:11], v[10:11], v[16:17] op_sel:[0,1] neg_lo:[0,1] neg_hi:[0,1]
	v_lshl_add_u64 v[20:21], s[0:1], 0, v[20:21]
	v_mul_f32_e32 v19, 0x45800000, v18
	v_cndmask_b32_e32 v18, v18, v19, vcc
	v_mul_f32_e32 v19, 0xbfb8aa3b, v22
	v_exp_f32_e32 v19, v19
	v_lshl_add_u64 v[20:21], v[20:21], 0, v[86:87]
	v_add_f32_e32 v19, 1.0, v19
	v_rcp_f32_e32 v28, v19
	v_add_f32_e32 v19, 1.0, v29
	v_rcp_f32_e32 v29, v19
	v_pk_mul_f32 v[8:9], v[8:9], v[18:19] op_sel_hi:[1,0]
	v_pk_mul_f32 v[22:23], v[28:29], v[22:23]
	v_lshlrev_b32_e32 v28, 16, v53
	v_and_b32_e32 v29, 0xffff0000, v53
	v_mul_f32_e32 v19, 0xbfb8aa3b, v28
	v_exp_f32_e32 v19, v19
	v_mul_f32_e32 v30, 0xbfb8aa3b, v29
	v_exp_f32_e32 v30, v30
	v_pk_mul_f32 v[8:9], v[44:45], v[8:9]
	v_add_f32_e32 v19, 1.0, v19
	v_pk_mul_f32 v[8:9], v[22:23], v[8:9]
	v_rcp_f32_e32 v22, v19
	v_add_f32_e32 v19, 1.0, v30
	v_rcp_f32_e32 v23, v19
	v_pk_mul_f32 v[10:11], v[10:11], v[18:19] op_sel_hi:[1,0]
	v_cvt_pk_bf16_f32 v8, v8, v9
	v_pk_mul_f32 v[10:11], v[46:47], v[10:11]
	v_pk_mul_f32 v[22:23], v[22:23], v[28:29]
	v_lshlrev_b32_e32 v28, 16, v54
	v_and_b32_e32 v29, 0xffff0000, v54
	v_mul_f32_e32 v19, 0xbfb8aa3b, v28
	v_exp_f32_e32 v19, v19
	v_mul_f32_e32 v30, 0xbfb8aa3b, v29
	v_exp_f32_e32 v30, v30
	v_pk_mul_f32 v[10:11], v[22:23], v[10:11]
	v_add_f32_e32 v19, 1.0, v19
	v_rcp_f32_e32 v22, v19
	v_add_f32_e32 v19, 1.0, v30
	v_rcp_f32_e32 v23, v19
	v_pk_add_f32 v[30:31], v[118:119], v[16:17] op_sel:[0,1] neg_lo:[0,1] neg_hi:[0,1]
	v_cvt_pk_bf16_f32 v9, v10, v11
	v_pk_mul_f32 v[30:31], v[30:31], v[18:19] op_sel_hi:[1,0]
	v_pk_mul_f32 v[22:23], v[22:23], v[28:29]
	v_lshlrev_b32_e32 v28, 16, v55
	v_and_b32_e32 v29, 0xffff0000, v55
	v_mul_f32_e32 v19, 0xbfb8aa3b, v28
	v_exp_f32_e32 v19, v19
	v_mul_f32_e32 v52, 0xbfb8aa3b, v29
	v_exp_f32_e32 v52, v52
	v_pk_mul_f32 v[30:31], v[36:37], v[30:31]
	v_add_f32_e32 v19, 1.0, v19
	v_pk_mul_f32 v[22:23], v[22:23], v[30:31]
	v_rcp_f32_e32 v30, v19
	v_add_f32_e32 v19, 1.0, v52
	v_rcp_f32_e32 v31, v19
	v_pk_add_f32 v[52:53], v[110:111], v[16:17] op_sel:[0,1] neg_lo:[0,1] neg_hi:[0,1]
	v_cvt_pk_bf16_f32 v10, v22, v23
	v_pk_mul_f32 v[52:53], v[52:53], v[18:19] op_sel_hi:[1,0]
	v_pk_mul_f32 v[28:29], v[30:31], v[28:29]
	v_pk_mul_f32 v[52:53], v[38:39], v[52:53]
	v_lshlrev_b32_e32 v22, 16, v48
	v_pk_mul_f32 v[28:29], v[28:29], v[52:53]
	v_and_b32_e32 v23, 0xffff0000, v48
	v_cvt_pk_bf16_f32 v11, v28, v29
	v_mul_f32_e32 v19, 0xbfb8aa3b, v22
	v_mul_f32_e32 v28, 0xbfb8aa3b, v23
	v_exp_f32_e32 v19, v19
	v_exp_f32_e32 v28, v28
	global_store_dwordx4 v[20:21], v[8:11], off
	s_nop 1
	v_add_f32_e32 v8, 1.0, v19
	v_add_f32_e32 v9, 1.0, v28
	v_rcp_f32_e32 v8, v8
	v_rcp_f32_e32 v9, v9
	v_pk_add_f32 v[10:11], v[142:143], v[16:17] op_sel:[0,1] neg_lo:[0,1] neg_hi:[0,1]
	v_pk_mul_f32 v[8:9], v[8:9], v[22:23]
	v_lshlrev_b32_e32 v22, 16, v49
	v_and_b32_e32 v23, 0xffff0000, v49
	v_pk_mul_f32 v[10:11], v[10:11], v[18:19] op_sel_hi:[1,0]
	v_mul_f32_e32 v19, 0xbfb8aa3b, v22
	v_mul_f32_e32 v28, 0xbfb8aa3b, v23
	v_exp_f32_e32 v19, v19
	v_exp_f32_e32 v28, v28
	v_pk_mul_f32 v[10:11], v[40:41], v[10:11]
	s_nop 0
	v_pk_mul_f32 v[8:9], v[8:9], v[10:11]
	v_add_f32_e32 v10, 1.0, v19
	v_add_f32_e32 v11, 1.0, v28
	v_rcp_f32_e32 v10, v10
	v_rcp_f32_e32 v11, v11
	v_pk_add_f32 v[28:29], v[122:123], v[16:17] op_sel:[0,1] neg_lo:[0,1] neg_hi:[0,1]
	v_cvt_pk_bf16_f32 v8, v8, v9
	v_pk_mul_f32 v[28:29], v[28:29], v[18:19] op_sel_hi:[1,0]
	v_pk_mul_f32 v[10:11], v[10:11], v[22:23]
	v_lshlrev_b32_e32 v22, 16, v50
	v_and_b32_e32 v23, 0xffff0000, v50
	v_mul_f32_e32 v19, 0xbfb8aa3b, v22
	v_exp_f32_e32 v19, v19
	v_mul_f32_e32 v30, 0xbfb8aa3b, v23
	v_exp_f32_e32 v30, v30
	v_pk_mul_f32 v[28:29], v[42:43], v[28:29]
	v_add_f32_e32 v19, 1.0, v19
	v_pk_mul_f32 v[10:11], v[10:11], v[28:29]
	v_rcp_f32_e32 v28, v19
	v_add_f32_e32 v19, 1.0, v30
	v_rcp_f32_e32 v29, v19
	v_pk_add_f32 v[30:31], v[108:109], v[16:17] op_sel:[0,1] neg_lo:[0,1] neg_hi:[0,1]
	v_pk_add_f32 v[16:17], v[104:105], v[16:17] op_sel:[0,1] neg_lo:[0,1] neg_hi:[0,1]
	v_pk_mul_f32 v[30:31], v[30:31], v[18:19] op_sel_hi:[1,0]
	v_pk_mul_f32 v[22:23], v[28:29], v[22:23]
	v_lshlrev_b32_e32 v28, 16, v51
	v_and_b32_e32 v29, 0xffff0000, v51
	v_mul_f32_e32 v19, 0xbfb8aa3b, v28
	v_exp_f32_e32 v19, v19
	v_mul_f32_e32 v48, 0xbfb8aa3b, v29
	v_exp_f32_e32 v48, v48
	v_pk_mul_f32 v[30:31], v[32:33], v[30:31]
	v_add_f32_e32 v19, 1.0, v19
	v_pk_mul_f32 v[22:23], v[22:23], v[30:31]
	v_rcp_f32_e32 v30, v19
	v_add_f32_e32 v19, 1.0, v48
	v_rcp_f32_e32 v31, v19
	v_pk_mul_f32 v[16:17], v[16:17], v[18:19] op_sel_hi:[1,0]
	v_cvt_pk_bf16_f32 v9, v10, v11
	v_pk_mul_f32 v[16:17], v[34:35], v[16:17]
	v_pk_mul_f32 v[18:19], v[30:31], v[28:29]
	v_cvt_pk_bf16_f32 v10, v22, v23
	v_pk_mul_f32 v[16:17], v[18:19], v[16:17]
	v_mad_i64_i32 v[104:105], s[2:3], v56, s77, v[172:173]
	v_cvt_pk_bf16_f32 v11, v16, v17
	global_store_dwordx4 v[20:21], v[8:11], off offset:256
	s_nop 1
	v_mad_i64_i32 v[8:9], s[2:3], v70, s77, v[172:173]
	v_lshl_add_u64 v[8:9], v[8:9], 0, v[86:87]
	s_waitcnt vmcnt(8)
	v_mov_b64_e32 v[62:63], v[204:205]
	v_mov_b64_e32 v[64:65], v[206:207]
	v_mov_b64_e32 v[66:67], v[208:209]
	v_mov_b64_e32 v[68:69], v[210:211]
	v_mad_i64_i32 v[8:9], s[2:3], v60, s77, v[172:173]
	v_lshl_add_u64 v[8:9], v[8:9], 0, v[86:87]
	v_mov_b64_e32 v[52:53], v[212:213]
	v_mov_b64_e32 v[54:55], v[214:215]
	v_mov_b64_e32 v[48:49], v[216:217]
	v_mov_b64_e32 v[50:51], v[218:219]
	v_mad_i64_i32 v[8:9], s[2:3], v58, s77, v[172:173]
	v_lshl_add_u64 v[8:9], v[8:9], 0, v[86:87]
	v_mov_b64_e32 v[28:29], v[220:221]
	v_mov_b64_e32 v[30:31], v[222:223]
	v_mov_b64_e32 v[20:21], v[224:225]
	v_mov_b64_e32 v[22:23], v[226:227]
	ds_read_b32 v9, v152 offset:512
	ds_read_b32 v11, v152 offset:1536
	ds_read_b32 v17, v152 offset:2560
	ds_read_b32 v19, v152 offset:3584
	ds_read_b32 v8, v152 offset:4608
	ds_read_b32 v10, v152 offset:5632
	ds_read_b32 v16, v152 offset:6656
	ds_read_b32 v18, v152 offset:7680
	v_lshlrev_b64 v[70:71], 11, v[70:71]
	v_lshl_add_u64 v[70:71], s[0:1], 0, v[70:71]
	s_waitcnt lgkmcnt(0)
	v_pk_add_f32 v[8:9], v[8:9], v[10:11]
	v_lshlrev_b64 v[60:61], 11, v[60:61]
	v_pk_add_f32 v[8:9], v[8:9], v[16:17]
	v_lshl_add_u64 v[60:61], s[0:1], 0, v[60:61]
	v_pk_add_f32 v[8:9], v[8:9], v[18:19]
	v_lshlrev_b32_e32 v108, 16, v62
	v_pk_mul_f32 v[106:107], v[8:9], s[16:17] op_sel_hi:[1,0]
	v_and_b32_e32 v109, 0xffff0000, v62
	v_fma_f32 v8, -v107, v107, v106
	v_max_f32_e32 v8, 0, v8
	v_add_f32_e32 v8, 0x358637bd, v8
	v_mul_f32_e32 v9, 0x4b800000, v8
	v_cmp_gt_f32_e32 vcc, s78, v8
	v_lshlrev_b32_e32 v62, 16, v63
	v_and_b32_e32 v63, 0xffff0000, v63
	v_cndmask_b32_e32 v8, v8, v9, vcc
	v_rsq_f32_e32 v57, v8
	v_lshl_add_u64 v[8:9], v[104:105], 0, v[86:87]
	v_pk_add_f32 v[24:25], v[24:25], v[106:107] op_sel:[0,1] neg_lo:[0,1] neg_hi:[0,1]
	v_pk_add_f32 v[26:27], v[26:27], v[106:107] op_sel:[0,1] neg_lo:[0,1] neg_hi:[0,1]
	v_mul_f32_e32 v59, 0x45800000, v57
	v_cndmask_b32_e32 v104, v57, v59, vcc
	v_mul_f32_e32 v57, 0xbfb8aa3b, v108
	v_exp_f32_e32 v57, v57
	v_mul_f32_e32 v59, 0xbfb8aa3b, v109
	v_exp_f32_e32 v59, v59
	v_pk_mul_f32 v[24:25], v[24:25], v[104:105] op_sel_hi:[1,0]
	v_add_f32_e32 v57, 1.0, v57
	v_rcp_f32_e32 v110, v57
	v_add_f32_e32 v57, 1.0, v59
	v_rcp_f32_e32 v111, v57
	v_mul_f32_e32 v57, 0xbfb8aa3b, v62
	v_exp_f32_e32 v57, v57
	v_mul_f32_e32 v59, 0xbfb8aa3b, v63
	v_exp_f32_e32 v59, v59
	v_pk_mul_f32 v[24:25], v[44:45], v[24:25]
	v_pk_mul_f32 v[108:109], v[110:111], v[108:109]
	v_add_f32_e32 v57, 1.0, v57
	v_pk_mul_f32 v[24:25], v[108:109], v[24:25]
	v_rcp_f32_e32 v108, v57
	v_add_f32_e32 v57, 1.0, v59
	v_rcp_f32_e32 v109, v57
	v_pk_mul_f32 v[26:27], v[26:27], v[104:105] op_sel_hi:[1,0]
	v_pk_add_f32 v[110:111], v[158:159], v[106:107] op_sel:[0,1] neg_lo:[0,1] neg_hi:[0,1]
	v_pk_mul_f32 v[26:27], v[46:47], v[26:27]
	v_pk_mul_f32 v[62:63], v[108:109], v[62:63]
	v_lshlrev_b32_e32 v108, 16, v64
	v_and_b32_e32 v109, 0xffff0000, v64
	v_mul_f32_e32 v57, 0xbfb8aa3b, v108
	v_exp_f32_e32 v57, v57
	v_mul_f32_e32 v59, 0xbfb8aa3b, v109
	v_exp_f32_e32 v59, v59
	v_pk_mul_f32 v[26:27], v[62:63], v[26:27]
	v_add_f32_e32 v57, 1.0, v57
	v_rcp_f32_e32 v62, v57
	v_add_f32_e32 v57, 1.0, v59
	v_lshlrev_b32_e32 v64, 16, v65
	v_rcp_f32_e32 v63, v57
	v_and_b32_e32 v65, 0xffff0000, v65
	v_mul_f32_e32 v57, 0xbfb8aa3b, v64
	v_exp_f32_e32 v57, v57
	v_mul_f32_e32 v59, 0xbfb8aa3b, v65
	v_exp_f32_e32 v59, v59
	v_pk_mul_f32 v[62:63], v[62:63], v[108:109]
	v_add_f32_e32 v57, 1.0, v57
	v_rcp_f32_e32 v108, v57
	v_add_f32_e32 v57, 1.0, v59
	v_pk_mul_f32 v[110:111], v[110:111], v[104:105] op_sel_hi:[1,0]
	v_rcp_f32_e32 v109, v57
	v_pk_mul_f32 v[110:111], v[36:37], v[110:111]
	v_cvt_pk_bf16_f32 v24, v24, v25
	v_pk_mul_f32 v[62:63], v[62:63], v[110:111]
	v_pk_add_f32 v[110:111], v[132:133], v[106:107] op_sel:[0,1] neg_lo:[0,1] neg_hi:[0,1]
	v_pk_mul_f32 v[64:65], v[108:109], v[64:65]
	v_pk_mul_f32 v[110:111], v[110:111], v[104:105] op_sel_hi:[1,0]
	v_cvt_pk_bf16_f32 v25, v26, v27
	v_pk_mul_f32 v[110:111], v[38:39], v[110:111]
	v_cvt_pk_bf16_f32 v26, v62, v63
	v_pk_mul_f32 v[64:65], v[64:65], v[110:111]
	v_lshl_add_u64 v[62:63], v[70:71], 0, v[86:87]
	v_cvt_pk_bf16_f32 v27, v64, v65
	v_lshlrev_b32_e32 v64, 16, v66
	v_and_b32_e32 v65, 0xffff0000, v66
	v_mul_f32_e32 v57, 0xbfb8aa3b, v64
	v_mul_f32_e32 v59, 0xbfb8aa3b, v65
	v_exp_f32_e32 v57, v57
	v_exp_f32_e32 v59, v59
	v_mov_b64_e32 v[16:17], v[228:229]
	v_mov_b64_e32 v[18:19], v[230:231]
	s_nop 0
	v_mov_b64_e32 v[8:9], v[232:233]
	v_mov_b64_e32 v[10:11], v[234:235]
	v_pk_add_f32 v[70:71], v[128:129], v[106:107] op_sel:[0,1] neg_lo:[0,1] neg_hi:[0,1]
	global_store_dwordx4 v[62:63], v[24:27], off
	v_pk_mul_f32 v[70:71], v[70:71], v[104:105] op_sel_hi:[1,0]
	s_nop 0
	v_add_f32_e32 v24, 1.0, v57
	v_add_f32_e32 v25, 1.0, v59
	v_rcp_f32_e32 v24, v24
	v_rcp_f32_e32 v25, v25
	v_pk_add_f32 v[26:27], v[162:163], v[106:107] op_sel:[0,1] neg_lo:[0,1] neg_hi:[0,1]
	v_pk_mul_f32 v[70:71], v[32:33], v[70:71]
	v_pk_mul_f32 v[26:27], v[26:27], v[104:105] op_sel_hi:[1,0]
	v_pk_mul_f32 v[24:25], v[24:25], v[64:65]
	v_lshlrev_b32_e32 v64, 16, v67
	v_and_b32_e32 v65, 0xffff0000, v67
	v_mul_f32_e32 v57, 0xbfb8aa3b, v64
	v_mul_f32_e32 v59, 0xbfb8aa3b, v65
	v_exp_f32_e32 v57, v57
	v_exp_f32_e32 v59, v59
	v_pk_mul_f32 v[26:27], v[40:41], v[26:27]
	v_pk_add_f32 v[66:67], v[146:147], v[106:107] op_sel:[0,1] neg_lo:[0,1] neg_hi:[0,1]
	v_pk_mul_f32 v[24:25], v[24:25], v[26:27]
	v_add_f32_e32 v26, 1.0, v57
	v_add_f32_e32 v27, 1.0, v59
	v_rcp_f32_e32 v26, v26
	v_rcp_f32_e32 v27, v27
	v_pk_mul_f32 v[66:67], v[66:67], v[104:105] op_sel_hi:[1,0]
	v_cvt_pk_bf16_f32 v24, v24, v25
	v_pk_mul_f32 v[66:67], v[42:43], v[66:67]
	v_pk_mul_f32 v[26:27], v[26:27], v[64:65]
	v_lshlrev_b32_e32 v64, 16, v68
	v_and_b32_e32 v65, 0xffff0000, v68
	v_mul_f32_e32 v57, 0xbfb8aa3b, v64
	v_exp_f32_e32 v57, v57
	v_mul_f32_e32 v59, 0xbfb8aa3b, v65
	v_exp_f32_e32 v59, v59
	v_pk_mul_f32 v[26:27], v[26:27], v[66:67]
	v_add_f32_e32 v57, 1.0, v57
	v_rcp_f32_e32 v66, v57
	v_add_f32_e32 v57, 1.0, v59
	v_rcp_f32_e32 v67, v57
	v_cvt_pk_bf16_f32 v25, v26, v27
	v_pk_mul_f32 v[64:65], v[66:67], v[64:65]
	v_lshlrev_b32_e32 v66, 16, v69
	v_and_b32_e32 v67, 0xffff0000, v69
	v_mul_f32_e32 v57, 0xbfb8aa3b, v66
	v_exp_f32_e32 v57, v57
	v_mul_f32_e32 v59, 0xbfb8aa3b, v67
	v_exp_f32_e32 v59, v59
	v_pk_mul_f32 v[64:65], v[64:65], v[70:71]
	v_add_f32_e32 v57, 1.0, v57
	v_rcp_f32_e32 v68, v57
	v_add_f32_e32 v57, 1.0, v59
	v_rcp_f32_e32 v69, v57
	v_pk_add_f32 v[70:71], v[112:113], v[106:107] op_sel:[0,1] neg_lo:[0,1] neg_hi:[0,1]
	v_cvt_pk_bf16_f32 v26, v64, v65
	v_pk_mul_f32 v[70:71], v[70:71], v[104:105] op_sel_hi:[1,0]
	v_pk_mul_f32 v[66:67], v[68:69], v[66:67]
	v_pk_mul_f32 v[70:71], v[34:35], v[70:71]
	v_ashrrev_i32_e32 v59, 31, v58
	v_pk_mul_f32 v[66:67], v[66:67], v[70:71]
	s_nop 0
	v_cvt_pk_bf16_f32 v27, v66, v67
	global_store_dwordx4 v[62:63], v[24:27], off offset:256
	ds_read_b32 v25, v152 offset:576
	ds_read_b32 v27, v152 offset:1600
	ds_read_b32 v63, v152 offset:2624
	ds_read_b32 v65, v152 offset:3648
	ds_read_b32 v24, v152 offset:4672
	ds_read_b32 v26, v152 offset:5696
	ds_read_b32 v62, v152 offset:6720
	ds_read_b32 v64, v152 offset:7744
	s_waitcnt lgkmcnt(0)
	v_pk_add_f32 v[24:25], v[24:25], v[26:27]
	s_nop 0
	v_pk_add_f32 v[24:25], v[24:25], v[62:63]
	v_lshlrev_b32_e32 v62, 16, v52
	v_pk_add_f32 v[24:25], v[24:25], v[64:65]
	v_and_b32_e32 v63, 0xffff0000, v52
	v_pk_mul_f32 v[24:25], v[24:25], s[16:17] op_sel_hi:[1,0]
	v_mul_f32_e32 v52, 0xbfb8aa3b, v63
	v_fma_f32 v26, -v25, v25, v24
	v_max_f32_e32 v26, 0, v26
	v_add_f32_e32 v26, 0x358637bd, v26
	v_mul_f32_e32 v27, 0x4b800000, v26
	v_cmp_gt_f32_e32 vcc, s78, v26
	v_exp_f32_e32 v52, v52
	v_pk_add_f32 v[12:13], v[12:13], v[24:25] op_sel:[0,1] neg_lo:[0,1] neg_hi:[0,1]
	v_cndmask_b32_e32 v26, v26, v27, vcc
	v_rsq_f32_e32 v26, v26
	v_pk_add_f32 v[14:15], v[14:15], v[24:25] op_sel:[0,1] neg_lo:[0,1] neg_hi:[0,1]
	v_mul_f32_e32 v27, 0x45800000, v26
	v_cndmask_b32_e32 v26, v26, v27, vcc
	v_mul_f32_e32 v27, 0xbfb8aa3b, v62
	v_exp_f32_e32 v27, v27
	s_nop 0
	v_add_f32_e32 v27, 1.0, v27
	v_rcp_f32_e32 v64, v27
	v_add_f32_e32 v27, 1.0, v52
	v_lshlrev_b32_e32 v52, 16, v53
	v_rcp_f32_e32 v65, v27
	v_pk_mul_f32 v[12:13], v[12:13], v[26:27] op_sel_hi:[1,0]
	v_and_b32_e32 v53, 0xffff0000, v53
	v_mul_f32_e32 v27, 0xbfb8aa3b, v52
	v_exp_f32_e32 v27, v27
	v_mul_f32_e32 v57, 0xbfb8aa3b, v53
	v_exp_f32_e32 v57, v57
	v_pk_mul_f32 v[12:13], v[44:45], v[12:13]
	v_pk_mul_f32 v[62:63], v[64:65], v[62:63]
	v_add_f32_e32 v27, 1.0, v27
	v_pk_mul_f32 v[12:13], v[62:63], v[12:13]
	v_rcp_f32_e32 v62, v27
	v_add_f32_e32 v27, 1.0, v57
	v_rcp_f32_e32 v63, v27
	v_pk_mul_f32 v[14:15], v[14:15], v[26:27] op_sel_hi:[1,0]
	v_pk_add_f32 v[64:65], v[124:125], v[24:25] op_sel:[0,1] neg_lo:[0,1] neg_hi:[0,1]
	v_pk_mul_f32 v[14:15], v[46:47], v[14:15]
	v_pk_mul_f32 v[52:53], v[62:63], v[52:53]
	v_lshlrev_b32_e32 v62, 16, v54
	v_and_b32_e32 v63, 0xffff0000, v54
	v_mul_f32_e32 v27, 0xbfb8aa3b, v62
	v_exp_f32_e32 v27, v27
	v_mul_f32_e32 v54, 0xbfb8aa3b, v63
	v_exp_f32_e32 v54, v54
	v_pk_mul_f32 v[14:15], v[52:53], v[14:15]
	v_add_f32_e32 v27, 1.0, v27
	v_rcp_f32_e32 v52, v27
	v_add_f32_e32 v27, 1.0, v54
	v_lshlrev_b32_e32 v54, 16, v55
	v_rcp_f32_e32 v53, v27
	v_pk_mul_f32 v[64:65], v[64:65], v[26:27] op_sel_hi:[1,0]
	v_and_b32_e32 v55, 0xffff0000, v55
	v_mul_f32_e32 v27, 0xbfb8aa3b, v54
	v_exp_f32_e32 v27, v27
	v_mul_f32_e32 v57, 0xbfb8aa3b, v55
	v_exp_f32_e32 v57, v57
	v_pk_mul_f32 v[52:53], v[52:53], v[62:63]
	v_add_f32_e32 v27, 1.0, v27
	v_rcp_f32_e32 v62, v27
	v_add_f32_e32 v27, 1.0, v57
	v_rcp_f32_e32 v63, v27
	v_pk_mul_f32 v[64:65], v[36:37], v[64:65]
	v_cvt_pk_bf16_f32 v12, v12, v13
	v_pk_mul_f32 v[52:53], v[52:53], v[64:65]
	v_pk_add_f32 v[64:65], v[100:101], v[24:25] op_sel:[0,1] neg_lo:[0,1] neg_hi:[0,1]
	v_pk_mul_f32 v[54:55], v[62:63], v[54:55]
	v_pk_mul_f32 v[64:65], v[64:65], v[26:27] op_sel_hi:[1,0]
	v_cvt_pk_bf16_f32 v13, v14, v15
	v_pk_mul_f32 v[64:65], v[38:39], v[64:65]
	v_cvt_pk_bf16_f32 v14, v52, v53
	v_pk_mul_f32 v[54:55], v[54:55], v[64:65]
	v_lshl_add_u64 v[52:53], v[60:61], 0, v[86:87]
	v_cvt_pk_bf16_f32 v15, v54, v55
	v_lshlrev_b32_e32 v54, 16, v48
	v_and_b32_e32 v55, 0xffff0000, v48
	v_mul_f32_e32 v27, 0xbfb8aa3b, v54
	v_mul_f32_e32 v48, 0xbfb8aa3b, v55
	v_exp_f32_e32 v27, v27
	v_exp_f32_e32 v48, v48
	global_store_dwordx4 v[52:53], v[12:15], off
	v_pk_add_f32 v[60:61], v[98:99], v[24:25] op_sel:[0,1] neg_lo:[0,1] neg_hi:[0,1]
	v_ashrrev_i32_e32 v57, 31, v56
	v_add_f32_e32 v12, 1.0, v27
	v_add_f32_e32 v13, 1.0, v48
	v_rcp_f32_e32 v12, v12
	v_rcp_f32_e32 v13, v13
	v_pk_add_f32 v[14:15], v[144:145], v[24:25] op_sel:[0,1] neg_lo:[0,1] neg_hi:[0,1]
	v_lshlrev_b32_e32 v48, 16, v49
	v_and_b32_e32 v49, 0xffff0000, v49
	v_pk_mul_f32 v[14:15], v[14:15], v[26:27] op_sel_hi:[1,0]
	v_pk_mul_f32 v[12:13], v[12:13], v[54:55]
	v_mul_f32_e32 v27, 0xbfb8aa3b, v48
	v_mul_f32_e32 v54, 0xbfb8aa3b, v49
	v_exp_f32_e32 v27, v27
	v_exp_f32_e32 v54, v54
	v_pk_mul_f32 v[14:15], v[40:41], v[14:15]
	s_nop 0
	v_pk_mul_f32 v[12:13], v[12:13], v[14:15]
	v_add_f32_e32 v14, 1.0, v27
	v_add_f32_e32 v15, 1.0, v54
	v_rcp_f32_e32 v14, v14
	v_rcp_f32_e32 v15, v15
	v_pk_add_f32 v[54:55], v[126:127], v[24:25] op_sel:[0,1] neg_lo:[0,1] neg_hi:[0,1]
	v_pk_add_f32 v[24:25], v[96:97], v[24:25] op_sel:[0,1] neg_lo:[0,1] neg_hi:[0,1]
	v_pk_mul_f32 v[54:55], v[54:55], v[26:27] op_sel_hi:[1,0]
	v_pk_mul_f32 v[14:15], v[14:15], v[48:49]
	v_lshlrev_b32_e32 v48, 16, v50
	v_and_b32_e32 v49, 0xffff0000, v50
	v_mul_f32_e32 v27, 0xbfb8aa3b, v48
	v_exp_f32_e32 v27, v27
	v_mul_f32_e32 v50, 0xbfb8aa3b, v49
	v_exp_f32_e32 v50, v50
	v_pk_mul_f32 v[54:55], v[42:43], v[54:55]
	v_add_f32_e32 v27, 1.0, v27
	v_pk_mul_f32 v[14:15], v[14:15], v[54:55]
	v_rcp_f32_e32 v54, v27
	v_add_f32_e32 v27, 1.0, v50
	v_rcp_f32_e32 v55, v27
	v_lshlrev_b32_e32 v50, 16, v51
	v_pk_mul_f32 v[60:61], v[60:61], v[26:27] op_sel_hi:[1,0]
	v_and_b32_e32 v51, 0xffff0000, v51
	v_mul_f32_e32 v27, 0xbfb8aa3b, v50
	v_pk_mul_f32 v[48:49], v[54:55], v[48:49]
	v_exp_f32_e32 v27, v27
	v_mul_f32_e32 v54, 0xbfb8aa3b, v51
	v_exp_f32_e32 v55, v54
	v_pk_mul_f32 v[60:61], v[32:33], v[60:61]
	v_add_f32_e32 v27, 1.0, v27
	v_rcp_f32_e32 v54, v27
	v_add_f32_e32 v27, 1.0, v55
	v_rcp_f32_e32 v55, v27
	v_pk_mul_f32 v[24:25], v[24:25], v[26:27] op_sel_hi:[1,0]
	v_pk_mul_f32 v[48:49], v[48:49], v[60:61]
	v_pk_mul_f32 v[24:25], v[34:35], v[24:25]
	v_pk_mul_f32 v[26:27], v[54:55], v[50:51]
	v_cvt_pk_bf16_f32 v12, v12, v13
	v_pk_mul_f32 v[24:25], v[26:27], v[24:25]
	v_cvt_pk_bf16_f32 v13, v14, v15
	v_cvt_pk_bf16_f32 v14, v48, v49
	v_cvt_pk_bf16_f32 v15, v24, v25
	global_store_dwordx4 v[52:53], v[12:15], off offset:256
	ds_read_b32 v13, v152 offset:640
	ds_read_b32 v15, v152 offset:1664
	ds_read_b32 v25, v152 offset:2688
	ds_read_b32 v27, v152 offset:3712
	ds_read_b32 v12, v152 offset:4736
	ds_read_b32 v14, v152 offset:5760
	ds_read_b32 v24, v152 offset:6784
	ds_read_b32 v26, v152 offset:7808
	s_waitcnt lgkmcnt(0)
	v_pk_add_f32 v[12:13], v[12:13], v[14:15]
	s_nop 0
	v_pk_add_f32 v[12:13], v[12:13], v[24:25]
	v_lshlrev_b64 v[24:25], 11, v[58:59]
	v_pk_add_f32 v[12:13], v[12:13], v[26:27]
	v_lshlrev_b32_e32 v26, 16, v28
	v_pk_mul_f32 v[12:13], v[12:13], s[16:17] op_sel_hi:[1,0]
	v_and_b32_e32 v27, 0xffff0000, v28
	v_fma_f32 v14, -v13, v13, v12
	v_max_f32_e32 v14, 0, v14
	v_add_f32_e32 v14, 0x358637bd, v14
	v_mul_f32_e32 v15, 0x4b800000, v14
	v_cmp_gt_f32_e32 vcc, s78, v14
	v_mul_f32_e32 v28, 0xbfb8aa3b, v27
	v_exp_f32_e32 v28, v28
	v_cndmask_b32_e32 v14, v14, v15, vcc
	v_rsq_f32_e32 v14, v14
	v_pk_add_f32 v[4:5], v[4:5], v[12:13] op_sel:[0,1] neg_lo:[0,1] neg_hi:[0,1]
	v_pk_add_f32 v[6:7], v[6:7], v[12:13] op_sel:[0,1] neg_lo:[0,1] neg_hi:[0,1]
	v_lshl_add_u64 v[24:25], s[0:1], 0, v[24:25]
	v_mul_f32_e32 v15, 0x45800000, v14
	v_cndmask_b32_e32 v14, v14, v15, vcc
	v_mul_f32_e32 v15, 0xbfb8aa3b, v26
	v_exp_f32_e32 v15, v15
	v_lshl_add_u64 v[24:25], v[24:25], 0, v[86:87]
	v_add_f32_e32 v15, 1.0, v15
	v_rcp_f32_e32 v48, v15
	v_add_f32_e32 v15, 1.0, v28
	v_rcp_f32_e32 v49, v15
	v_lshlrev_b32_e32 v28, 16, v29
	v_pk_mul_f32 v[4:5], v[4:5], v[14:15] op_sel_hi:[1,0]
	v_and_b32_e32 v29, 0xffff0000, v29
	v_mul_f32_e32 v15, 0xbfb8aa3b, v28
	v_pk_mul_f32 v[26:27], v[48:49], v[26:27]
	v_exp_f32_e32 v15, v15
	v_mul_f32_e32 v48, 0xbfb8aa3b, v29
	v_exp_f32_e32 v48, v48
	v_pk_mul_f32 v[4:5], v[44:45], v[4:5]
	v_add_f32_e32 v15, 1.0, v15
	v_pk_mul_f32 v[4:5], v[26:27], v[4:5]
	v_rcp_f32_e32 v26, v15
	v_add_f32_e32 v15, 1.0, v48
	v_rcp_f32_e32 v27, v15
	v_pk_mul_f32 v[6:7], v[6:7], v[14:15] op_sel_hi:[1,0]
	v_pk_add_f32 v[48:49], v[94:95], v[12:13] op_sel:[0,1] neg_lo:[0,1] neg_hi:[0,1]
	v_pk_mul_f32 v[6:7], v[46:47], v[6:7]
	v_pk_mul_f32 v[26:27], v[26:27], v[28:29]
	v_lshlrev_b32_e32 v28, 16, v30
	v_and_b32_e32 v29, 0xffff0000, v30
	v_mul_f32_e32 v15, 0xbfb8aa3b, v28
	v_exp_f32_e32 v15, v15
	v_mul_f32_e32 v30, 0xbfb8aa3b, v29
	v_exp_f32_e32 v30, v30
	v_pk_mul_f32 v[6:7], v[26:27], v[6:7]
	v_add_f32_e32 v15, 1.0, v15
	v_rcp_f32_e32 v26, v15
	v_add_f32_e32 v15, 1.0, v30
	v_rcp_f32_e32 v27, v15
	v_pk_mul_f32 v[48:49], v[48:49], v[14:15] op_sel_hi:[1,0]
	v_cvt_pk_bf16_f32 v4, v4, v5
	v_pk_mul_f32 v[48:49], v[36:37], v[48:49]
	v_pk_mul_f32 v[26:27], v[26:27], v[28:29]
	v_lshlrev_b32_e32 v28, 16, v31
	v_and_b32_e32 v29, 0xffff0000, v31
	v_mul_f32_e32 v15, 0xbfb8aa3b, v28
	v_exp_f32_e32 v15, v15
	v_mul_f32_e32 v30, 0xbfb8aa3b, v29
	v_exp_f32_e32 v31, v30
	v_pk_mul_f32 v[26:27], v[26:27], v[48:49]
	v_add_f32_e32 v15, 1.0, v15
	v_rcp_f32_e32 v30, v15
	v_add_f32_e32 v15, 1.0, v31
	v_rcp_f32_e32 v31, v15
	v_pk_add_f32 v[48:49], v[92:93], v[12:13] op_sel:[0,1] neg_lo:[0,1] neg_hi:[0,1]
	v_cvt_pk_bf16_f32 v5, v6, v7
	v_cvt_pk_bf16_f32 v6, v26, v27
	v_lshlrev_b32_e32 v26, 16, v20
	v_and_b32_e32 v27, 0xffff0000, v20
	v_pk_mul_f32 v[48:49], v[48:49], v[14:15] op_sel_hi:[1,0]
	v_mul_f32_e32 v15, 0xbfb8aa3b, v26
	v_mul_f32_e32 v20, 0xbfb8aa3b, v27
	v_exp_f32_e32 v15, v15
	v_exp_f32_e32 v20, v20
	v_pk_mul_f32 v[48:49], v[38:39], v[48:49]
	v_pk_mul_f32 v[28:29], v[30:31], v[28:29]
	s_nop 0
	v_pk_mul_f32 v[28:29], v[28:29], v[48:49]
	s_nop 0
	v_cvt_pk_bf16_f32 v7, v28, v29
	global_store_dwordx4 v[24:25], v[4:7], off
	v_pk_add_f32 v[28:29], v[88:89], v[12:13] op_sel:[0,1] neg_lo:[0,1] neg_hi:[0,1]
	s_nop 0
	v_add_f32_e32 v4, 1.0, v15
	v_add_f32_e32 v5, 1.0, v20
	v_rcp_f32_e32 v4, v4
	v_rcp_f32_e32 v5, v5
	v_pk_add_f32 v[6:7], v[102:103], v[12:13] op_sel:[0,1] neg_lo:[0,1] neg_hi:[0,1]
	v_lshlrev_b32_e32 v20, 16, v21
	v_and_b32_e32 v21, 0xffff0000, v21
	v_pk_mul_f32 v[6:7], v[6:7], v[14:15] op_sel_hi:[1,0]
	v_pk_mul_f32 v[4:5], v[4:5], v[26:27]
	v_mul_f32_e32 v15, 0xbfb8aa3b, v20
	v_mul_f32_e32 v26, 0xbfb8aa3b, v21
	v_exp_f32_e32 v15, v15
	v_exp_f32_e32 v26, v26
	v_pk_mul_f32 v[6:7], v[40:41], v[6:7]
	s_nop 0
	v_pk_mul_f32 v[4:5], v[4:5], v[6:7]
	v_add_f32_e32 v6, 1.0, v15
	v_add_f32_e32 v7, 1.0, v26
	v_rcp_f32_e32 v6, v6
	v_rcp_f32_e32 v7, v7
	v_pk_add_f32 v[26:27], v[90:91], v[12:13] op_sel:[0,1] neg_lo:[0,1] neg_hi:[0,1]
	v_pk_add_f32 v[12:13], v[78:79], v[12:13] op_sel:[0,1] neg_lo:[0,1] neg_hi:[0,1]
	v_pk_mul_f32 v[26:27], v[26:27], v[14:15] op_sel_hi:[1,0]
	v_pk_mul_f32 v[6:7], v[6:7], v[20:21]
	v_lshlrev_b32_e32 v20, 16, v22
	v_and_b32_e32 v21, 0xffff0000, v22
	v_mul_f32_e32 v15, 0xbfb8aa3b, v20
	v_exp_f32_e32 v15, v15
	v_mul_f32_e32 v22, 0xbfb8aa3b, v21
	v_exp_f32_e32 v22, v22
	v_pk_mul_f32 v[26:27], v[42:43], v[26:27]
	v_add_f32_e32 v15, 1.0, v15
	v_pk_mul_f32 v[6:7], v[6:7], v[26:27]
	v_rcp_f32_e32 v26, v15
	v_add_f32_e32 v15, 1.0, v22
	v_rcp_f32_e32 v27, v15
	v_lshlrev_b32_e32 v22, 16, v23
	v_pk_mul_f32 v[28:29], v[28:29], v[14:15] op_sel_hi:[1,0]
	v_and_b32_e32 v23, 0xffff0000, v23
	v_mul_f32_e32 v15, 0xbfb8aa3b, v22
	v_pk_mul_f32 v[20:21], v[26:27], v[20:21]
	v_exp_f32_e32 v15, v15
	v_mul_f32_e32 v26, 0xbfb8aa3b, v23
	v_exp_f32_e32 v27, v26
	v_pk_mul_f32 v[28:29], v[32:33], v[28:29]
	v_add_f32_e32 v15, 1.0, v15
	v_rcp_f32_e32 v26, v15
	v_add_f32_e32 v15, 1.0, v27
	v_rcp_f32_e32 v27, v15
	v_pk_mul_f32 v[12:13], v[12:13], v[14:15] op_sel_hi:[1,0]
	v_pk_mul_f32 v[20:21], v[20:21], v[28:29]
	v_pk_mul_f32 v[12:13], v[34:35], v[12:13]
	v_pk_mul_f32 v[14:15], v[26:27], v[22:23]
	v_cvt_pk_bf16_f32 v4, v4, v5
	v_pk_mul_f32 v[12:13], v[14:15], v[12:13]
	v_cvt_pk_bf16_f32 v5, v6, v7
	v_cvt_pk_bf16_f32 v6, v20, v21
	v_cvt_pk_bf16_f32 v7, v12, v13
	global_store_dwordx4 v[24:25], v[4:7], off offset:256
	ds_read_b32 v5, v152 offset:704
	ds_read_b32 v7, v152 offset:1728
	ds_read_b32 v13, v152 offset:2752
	ds_read_b32 v15, v152 offset:3776
	ds_read_b32 v4, v152 offset:4800
	ds_read_b32 v6, v152 offset:5824
	ds_read_b32 v12, v152 offset:6848
	ds_read_b32 v14, v152 offset:7872
	s_waitcnt lgkmcnt(0)
	v_pk_add_f32 v[4:5], v[4:5], v[6:7]
	s_nop 0
	v_pk_add_f32 v[4:5], v[4:5], v[12:13]
	v_lshlrev_b64 v[12:13], 11, v[56:57]
	v_pk_add_f32 v[4:5], v[4:5], v[14:15]
	v_lshlrev_b32_e32 v14, 16, v16
	v_pk_mul_f32 v[4:5], v[4:5], s[16:17] op_sel_hi:[1,0]
	v_and_b32_e32 v15, 0xffff0000, v16
	v_fma_f32 v6, -v5, v5, v4
	v_max_f32_e32 v6, 0, v6
	v_add_f32_e32 v6, 0x358637bd, v6
	v_mul_f32_e32 v7, 0x4b800000, v6
	v_cmp_gt_f32_e32 vcc, s78, v6
	v_mul_f32_e32 v16, 0xbfb8aa3b, v15
	v_exp_f32_e32 v16, v16
	v_cndmask_b32_e32 v6, v6, v7, vcc
	v_rsq_f32_e32 v6, v6
	v_pk_add_f32 v[0:1], v[0:1], v[4:5] op_sel:[0,1] neg_lo:[0,1] neg_hi:[0,1]
	v_pk_add_f32 v[2:3], v[2:3], v[4:5] op_sel:[0,1] neg_lo:[0,1] neg_hi:[0,1]
	v_lshl_add_u64 v[12:13], s[0:1], 0, v[12:13]
	v_mul_f32_e32 v7, 0x45800000, v6
	v_cndmask_b32_e32 v6, v6, v7, vcc
	v_mul_f32_e32 v7, 0xbfb8aa3b, v14
	v_exp_f32_e32 v7, v7
	v_lshl_add_u64 v[12:13], v[12:13], 0, v[86:87]
	v_add_f32_e32 v7, 1.0, v7
	v_rcp_f32_e32 v20, v7
	v_add_f32_e32 v7, 1.0, v16
	v_rcp_f32_e32 v21, v7
	v_lshlrev_b32_e32 v16, 16, v17
	v_pk_mul_f32 v[0:1], v[0:1], v[6:7] op_sel_hi:[1,0]
	v_and_b32_e32 v17, 0xffff0000, v17
	v_mul_f32_e32 v7, 0xbfb8aa3b, v16
	v_pk_mul_f32 v[14:15], v[20:21], v[14:15]
	v_exp_f32_e32 v7, v7
	v_mul_f32_e32 v20, 0xbfb8aa3b, v17
	v_exp_f32_e32 v20, v20
	v_pk_mul_f32 v[0:1], v[44:45], v[0:1]
	v_add_f32_e32 v7, 1.0, v7
	v_pk_mul_f32 v[0:1], v[14:15], v[0:1]
	v_rcp_f32_e32 v14, v7
	v_add_f32_e32 v7, 1.0, v20
	v_rcp_f32_e32 v15, v7
	v_pk_mul_f32 v[2:3], v[2:3], v[6:7] op_sel_hi:[1,0]
	v_pk_add_f32 v[20:21], v[84:85], v[4:5] op_sel:[0,1] neg_lo:[0,1] neg_hi:[0,1]
	v_pk_mul_f32 v[2:3], v[46:47], v[2:3]
	v_pk_mul_f32 v[14:15], v[14:15], v[16:17]
	v_lshlrev_b32_e32 v16, 16, v18
	v_and_b32_e32 v17, 0xffff0000, v18
	v_mul_f32_e32 v7, 0xbfb8aa3b, v16
	v_exp_f32_e32 v7, v7
	v_mul_f32_e32 v18, 0xbfb8aa3b, v17
	v_exp_f32_e32 v18, v18
	v_pk_mul_f32 v[2:3], v[14:15], v[2:3]
	v_add_f32_e32 v7, 1.0, v7
	v_rcp_f32_e32 v14, v7
	v_add_f32_e32 v7, 1.0, v18
	v_rcp_f32_e32 v15, v7
	v_pk_mul_f32 v[20:21], v[20:21], v[6:7] op_sel_hi:[1,0]
	v_cvt_pk_bf16_f32 v0, v0, v1
	v_pk_mul_f32 v[20:21], v[36:37], v[20:21]
	v_pk_mul_f32 v[14:15], v[14:15], v[16:17]
	v_lshlrev_b32_e32 v16, 16, v19
	v_and_b32_e32 v17, 0xffff0000, v19
	v_mul_f32_e32 v7, 0xbfb8aa3b, v16
	v_exp_f32_e32 v7, v7
	v_mul_f32_e32 v18, 0xbfb8aa3b, v17
	v_exp_f32_e32 v19, v18
	v_pk_mul_f32 v[14:15], v[14:15], v[20:21]
	v_add_f32_e32 v7, 1.0, v7
	v_rcp_f32_e32 v18, v7
	v_add_f32_e32 v7, 1.0, v19
	v_rcp_f32_e32 v19, v7
	v_pk_add_f32 v[20:21], v[76:77], v[4:5] op_sel:[0,1] neg_lo:[0,1] neg_hi:[0,1]
	v_cvt_pk_bf16_f32 v1, v2, v3
	v_cvt_pk_bf16_f32 v2, v14, v15
	v_lshlrev_b32_e32 v14, 16, v8
	v_and_b32_e32 v15, 0xffff0000, v8
	v_pk_mul_f32 v[20:21], v[20:21], v[6:7] op_sel_hi:[1,0]
	v_mul_f32_e32 v7, 0xbfb8aa3b, v14
	v_mul_f32_e32 v8, 0xbfb8aa3b, v15
	v_exp_f32_e32 v7, v7
	v_exp_f32_e32 v8, v8
	v_pk_mul_f32 v[20:21], v[38:39], v[20:21]
	v_pk_mul_f32 v[16:17], v[18:19], v[16:17]
	s_nop 0
	v_pk_mul_f32 v[16:17], v[16:17], v[20:21]
	s_nop 0
	v_cvt_pk_bf16_f32 v3, v16, v17
	global_store_dwordx4 v[12:13], v[0:3], off
	v_pk_add_f32 v[16:17], v[74:75], v[4:5] op_sel:[0,1] neg_lo:[0,1] neg_hi:[0,1]
	s_nop 0
	v_add_f32_e32 v0, 1.0, v7
	v_add_f32_e32 v1, 1.0, v8
	v_rcp_f32_e32 v0, v0
	v_rcp_f32_e32 v1, v1
	v_pk_add_f32 v[2:3], v[82:83], v[4:5] op_sel:[0,1] neg_lo:[0,1] neg_hi:[0,1]
	v_lshlrev_b32_e32 v8, 16, v9
	v_and_b32_e32 v9, 0xffff0000, v9
	v_pk_mul_f32 v[2:3], v[2:3], v[6:7] op_sel_hi:[1,0]
	v_pk_mul_f32 v[0:1], v[0:1], v[14:15]
	v_mul_f32_e32 v7, 0xbfb8aa3b, v8
	v_mul_f32_e32 v14, 0xbfb8aa3b, v9
	v_exp_f32_e32 v7, v7
	v_exp_f32_e32 v14, v14
	v_pk_mul_f32 v[2:3], v[40:41], v[2:3]
	s_nop 0
	v_pk_mul_f32 v[0:1], v[0:1], v[2:3]
	v_add_f32_e32 v2, 1.0, v7
	v_add_f32_e32 v3, 1.0, v14
	v_rcp_f32_e32 v2, v2
	v_rcp_f32_e32 v3, v3
	v_pk_add_f32 v[14:15], v[80:81], v[4:5] op_sel:[0,1] neg_lo:[0,1] neg_hi:[0,1]
	v_pk_add_f32 v[4:5], v[72:73], v[4:5] op_sel:[0,1] neg_lo:[0,1] neg_hi:[0,1]
	v_pk_mul_f32 v[14:15], v[14:15], v[6:7] op_sel_hi:[1,0]
	v_pk_mul_f32 v[2:3], v[2:3], v[8:9]
	v_lshlrev_b32_e32 v8, 16, v10
	v_and_b32_e32 v9, 0xffff0000, v10
	v_mul_f32_e32 v7, 0xbfb8aa3b, v8
	v_exp_f32_e32 v7, v7
	v_mul_f32_e32 v10, 0xbfb8aa3b, v9
	v_exp_f32_e32 v10, v10
	v_pk_mul_f32 v[14:15], v[42:43], v[14:15]
	v_add_f32_e32 v7, 1.0, v7
	v_pk_mul_f32 v[2:3], v[2:3], v[14:15]
	v_rcp_f32_e32 v14, v7
	v_add_f32_e32 v7, 1.0, v10
	v_rcp_f32_e32 v15, v7
	v_lshlrev_b32_e32 v10, 16, v11
	v_pk_mul_f32 v[16:17], v[16:17], v[6:7] op_sel_hi:[1,0]
	v_and_b32_e32 v11, 0xffff0000, v11
	v_mul_f32_e32 v7, 0xbfb8aa3b, v10
	v_pk_mul_f32 v[8:9], v[14:15], v[8:9]
	v_exp_f32_e32 v7, v7
	v_mul_f32_e32 v14, 0xbfb8aa3b, v11
	v_exp_f32_e32 v15, v14
	v_pk_mul_f32 v[16:17], v[32:33], v[16:17]
	v_add_f32_e32 v7, 1.0, v7
	v_rcp_f32_e32 v14, v7
	v_add_f32_e32 v7, 1.0, v15
	v_rcp_f32_e32 v15, v7
	v_pk_mul_f32 v[4:5], v[4:5], v[6:7] op_sel_hi:[1,0]
	v_pk_mul_f32 v[8:9], v[8:9], v[16:17]
	v_pk_mul_f32 v[4:5], v[34:35], v[4:5]
	v_pk_mul_f32 v[6:7], v[14:15], v[10:11]
	v_cvt_pk_bf16_f32 v0, v0, v1
	v_pk_mul_f32 v[4:5], v[6:7], v[4:5]
	v_cvt_pk_bf16_f32 v1, v2, v3
	v_cvt_pk_bf16_f32 v2, v8, v9
	v_cvt_pk_bf16_f32 v3, v4, v5
	global_store_dwordx4 v[12:13], v[0:3], off offset:256
	s_cbranch_scc1 .LBB0_679
	s_branch .Lpadskip_0
	s_nop 0
	s_nop 0
	s_nop 0
	s_nop 0
	s_nop 0
	s_nop 0
	s_nop 0
	s_nop 0
	s_nop 0
	s_nop 0
	s_nop 0
	s_nop 0
	s_nop 0
	s_nop 0
	s_nop 0
	s_nop 0
	s_nop 0
	s_nop 0
	s_nop 0
	s_nop 0
	s_nop 0
	s_nop 0
	s_nop 0
	s_nop 0
	s_nop 0
	s_nop 0
	s_nop 0
	s_nop 0
	s_nop 0
	s_nop 0
	s_nop 0
	s_nop 0
	s_nop 0
	s_nop 0
	s_nop 0
	s_nop 0
	s_nop 0
	s_nop 0
.Lpadskip_0:
.LBB0_615:
	s_lshl_b32 s0, s18, 6
	s_lshl_b32 s1, s18, 8
	s_and_b32 s0, s0, 0xffffe000
	s_and_b32 s1, s1, 0x1f00
	s_or_b32 s20, s0, s1
	s_ashr_i32 s19, s18, 31
	s_bfe_u32 s33, s18, 0x20005
	s_ashr_i32 s21, s20, 31
	s_lshl_b64 s[0:1], s[18:19], 2
	s_add_u32 s0, s37, s0
	s_addc_u32 s1, s38, s1
	v_readfirstlane_b32 s81, v182
	global_load_dword v2, v153, s[0:1]
	s_lshl_b64 s[22:23], s[18:19], 10
	s_add_u32 s22, s39, s22
	s_addc_u32 s23, s40, s23
	v_and_b32_e32 v4, 63, v182
	v_lshlrev_b32_e32 v5, 4, v4
	v_lshlrev_b32_e32 v152, 3, v4
	global_load_dwordx4 v[74:77], v5, s[22:23]
	s_ashr_i32 s2, s81, 6
	s_lshl_b64 s[22:23], s[20:21], 11
	s_lshl_b32 s24, s2, 16
	s_add_u32 s22, s22, s24
	s_addc_u32 s23, s23, 0
	s_lshl_b32 s25, s33, 9
	s_add_u32 s22, s22, s25
	s_addc_u32 s23, s23, 0
	s_add_u32 s22, s22, s65
	s_addc_u32 s23, s23, s68
	s_sub_u32 s22, s22, 0x3800
	s_subb_u32 s23, s23, 0
	global_load_dwordx2 v[10:11], v152, s[22:23] offset:0
	global_load_dwordx2 v[12:13], v152, s[22:23] offset:2048
	s_add_u32 s22, s22, 0x1000
	s_addc_u32 s23, s23, 0
	global_load_dwordx2 v[14:15], v152, s[22:23] offset:0
	global_load_dwordx2 v[16:17], v152, s[22:23] offset:2048
	s_add_u32 s22, s22, 0x1000
	s_addc_u32 s23, s23, 0
	global_load_dwordx2 v[18:19], v152, s[22:23] offset:0
	global_load_dwordx2 v[20:21], v152, s[22:23] offset:2048
	s_add_u32 s22, s22, 0x1000
	s_addc_u32 s23, s23, 0
	global_load_dwordx2 v[22:23], v152, s[22:23] offset:0
	global_load_dwordx2 v[24:25], v152, s[22:23] offset:2048
	s_add_u32 s22, s22, 0x1000
	s_addc_u32 s23, s23, 0
	global_load_dwordx2 v[26:27], v152, s[22:23] offset:0
	global_load_dwordx2 v[28:29], v152, s[22:23] offset:2048
	s_add_u32 s22, s22, 0x1000
	s_addc_u32 s23, s23, 0
	global_load_dwordx2 v[30:31], v152, s[22:23] offset:0
	global_load_dwordx2 v[32:33], v152, s[22:23] offset:2048
	s_add_u32 s22, s22, 0x1000
	s_addc_u32 s23, s23, 0
	global_load_dwordx2 v[34:35], v152, s[22:23] offset:0
	global_load_dwordx2 v[36:37], v152, s[22:23] offset:2048
	s_add_u32 s22, s22, 0x1000
	s_addc_u32 s23, s23, 0
	global_load_dwordx2 v[38:39], v152, s[22:23] offset:0
	global_load_dwordx2 v[40:41], v152, s[22:23] offset:2048
	s_add_u32 s22, s22, 0x1000
	s_addc_u32 s23, s23, 0
	global_load_dwordx2 v[42:43], v152, s[22:23] offset:0
	global_load_dwordx2 v[44:45], v152, s[22:23] offset:2048
	s_add_u32 s22, s22, 0x1000
	s_addc_u32 s23, s23, 0
	global_load_dwordx2 v[46:47], v152, s[22:23] offset:0
	global_load_dwordx2 v[48:49], v152, s[22:23] offset:2048
	s_add_u32 s22, s22, 0x1000
	s_addc_u32 s23, s23, 0
	global_load_dwordx2 v[50:51], v152, s[22:23] offset:0
	global_load_dwordx2 v[52:53], v152, s[22:23] offset:2048
	s_add_u32 s22, s22, 0x1000
	s_addc_u32 s23, s23, 0
	global_load_dwordx2 v[54:55], v152, s[22:23] offset:0
	global_load_dwordx2 v[56:57], v152, s[22:23] offset:2048
	s_add_u32 s22, s22, 0x1000
	s_addc_u32 s23, s23, 0
	global_load_dwordx2 v[58:59], v152, s[22:23] offset:0
	global_load_dwordx2 v[60:61], v152, s[22:23] offset:2048
	s_add_u32 s22, s22, 0x1000
	s_addc_u32 s23, s23, 0
	global_load_dwordx2 v[62:63], v152, s[22:23] offset:0
	global_load_dwordx2 v[64:65], v152, s[22:23] offset:2048
	s_add_u32 s22, s22, 0x1000
	s_addc_u32 s23, s23, 0
	global_load_dwordx2 v[66:67], v152, s[22:23] offset:0
	global_load_dwordx2 v[68:69], v152, s[22:23] offset:2048
	s_add_u32 s22, s22, 0x1000
	s_addc_u32 s23, s23, 0
	global_load_dwordx2 v[70:71], v152, s[22:23] offset:0
	global_load_dwordx2 v[72:73], v152, s[22:23] offset:2048
	s_movk_i32 s0, 0x100
	v_mov_b32_e32 v1, v182
	v_cmp_gt_i32_e32 vcc, s0, v1
	s_barrier
	s_and_saveexec_b64 s[0:1], vcc
	s_cbranch_execz .LBB0_617
	v_add_u32_e32 v4, s20, v1
	v_ashrrev_i32_e32 v5, 31, v4
	v_lshlrev_b64 v[4:5], 4, v[4:5]
	v_lshl_or_b32 v4, s33, 2, v4
	v_lshl_add_u64 v[6:7], s[8:9], 0, v[4:5]
	global_load_dword v3, v[6:7], off
	v_lshl_add_u64 v[6:7], s[4:5], 0, v[4:5]
	global_load_dword v6, v[6:7], off
	v_lshl_add_u64 v[4:5], s[6:7], 0, v[4:5]
	global_load_dword v4, v[4:5], off
	s_waitcnt vmcnt(0)
	v_max_f32_e32 v5, v2, v2
	v_lshl_add_u32 v1, v1, 2, 0
	v_add_u32_e32 v9, 0x20800, v1
	v_add_u32_e32 v7, 0x20000, v1
	v_add_u32_e32 v8, 0x20400, v1
	v_add_u32_e32 v1, 0x20c00, v1
	s_waitcnt vmcnt(2)
	v_max_f32_e32 v3, v3, v3
	v_max_f32_e32 v3, v5, v3
	v_sub_f32_e32 v2, v2, v3
	s_waitcnt vmcnt(1)
	v_add_f32_e32 v5, v6, v3
	v_mul_f32_e32 v2, 0x3fb8aa3b, v2
	v_mul_f32_e32 v5, 0xbfb8aa3b, v5
	v_exp_f32_e32 v2, v2
	v_exp_f32_e32 v5, v5
	s_waitcnt vmcnt(0)
	ds_write_b32 v9, v4
	ds_write_b32 v7, v3
	ds_write_b32 v8, v2
	ds_write_b32 v1, v5

.LBB0_677:
	s_or_b64 exec, exec, s[0:1]
	v_add_u32_e32 v46, 0xc0, v152
	s_waitcnt lgkmcnt(1)
	ds_read2st64_b32 v[44:45], v46 offset0:2 offset1:6
	s_waitcnt lgkmcnt(1)
	ds_read2st64_b32 v[46:47], v46 offset0:10 offset1:14
	ds_read_b32 v48, v174 offset:704
	ds_read_b32 v49, v175 offset:704
	ds_read_b32 v50, v176 offset:704
	s_waitcnt lgkmcnt(4)
	v_add_f32_e32 v44, v44, v45
	s_waitcnt lgkmcnt(3)
	v_add_f32_e32 v44, v44, v46
	v_add_f32_e32 v44, v44, v47
	s_waitcnt lgkmcnt(1)
	v_fmac_f32_e32 v44, v48, v49
	s_waitcnt lgkmcnt(0)
	v_max_f32_e32 v45, v50, v50
	v_max_f32_e64 v44, |v44|, v45
	v_rcp_f32_e32 v44, v44
	v_and_b32_e32 v50, 0xffff0000, v86
	v_mul_f32_e32 v50, 0xbfb8aa3b, v50
	v_exp_f32_e32 v51, v50
	v_pk_mul_f32 v[42:43], v[42:43], v[44:45] op_sel_hi:[1,0]
	v_pk_mul_f32 v[40:41], v[40:41], v[44:45] op_sel_hi:[1,0]
	v_pk_mul_f32 v[46:47], v[2:3], v[44:45] op_sel_hi:[1,0]
	v_pk_mul_f32 v[48:49], v[0:1], v[44:45] op_sel_hi:[1,0]
	v_lshlrev_b32_e32 v45, 16, v86
	v_mul_f32_e32 v45, 0xbfb8aa3b, v45
	v_exp_f32_e32 v45, v45
	v_lshlrev_b32_e32 v2, 16, v84
	v_and_b32_e32 v3, 0xffff0000, v84
	v_mul_f32_e32 v2, 0xbfb8aa3b, v2
	v_add_f32_e32 v45, 1.0, v45
	v_rcp_f32_e32 v50, v45
	v_add_f32_e32 v45, 1.0, v51
	v_lshlrev_b32_e32 v51, 16, v87
	v_mul_f32_e32 v51, 0xbfb8aa3b, v51
	v_exp_f32_e32 v52, v51
	v_and_b32_e32 v51, 0xffff0000, v87
	v_mul_f32_e32 v51, 0xbfb8aa3b, v51
	v_mul_f32_e32 v3, 0xbfb8aa3b, v3
	v_exp_f32_e32 v53, v51
	v_exp_f32_e32 v2, v2
	v_exp_f32_e32 v3, v3
	v_rcp_f32_e32 v51, v45
	v_add_f32_e32 v45, 1.0, v52
	v_rcp_f32_e32 v52, v45
	v_add_f32_e32 v45, 1.0, v53
	v_add_f32_e32 v0, 1.0, v2
	v_add_f32_e32 v1, 1.0, v3
	v_lshlrev_b32_e32 v2, 16, v85
	v_and_b32_e32 v3, 0xffff0000, v85
	v_rcp_f32_e32 v53, v45
	v_pk_mul_f32 v[84:85], v[50:51], v[48:49]
	v_pk_mul_f32 v[38:39], v[38:39], v[44:45] op_sel_hi:[1,0]
	v_pk_mul_f32 v[36:37], v[36:37], v[44:45] op_sel_hi:[1,0]
	v_pk_mul_f32 v[34:35], v[34:35], v[44:45] op_sel_hi:[1,0]
	v_lshlrev_b32_e32 v45, 16, v80
	v_and_b32_e32 v50, 0xffff0000, v80
	v_mul_f32_e32 v45, 0xbfb8aa3b, v45
	v_mul_f32_e32 v50, 0xbfb8aa3b, v50
	v_exp_f32_e32 v45, v45
	v_exp_f32_e32 v50, v50
	v_mul_f32_e32 v2, 0xbfb8aa3b, v2
	v_mul_f32_e32 v3, 0xbfb8aa3b, v3
	v_pk_mul_f32 v[76:77], v[52:53], v[46:47]
	v_pk_mul_f32 v[32:33], v[32:33], v[44:45] op_sel_hi:[1,0]
	v_add_f32_e32 v44, 1.0, v45
	v_add_f32_e32 v45, 1.0, v50
	v_lshlrev_b32_e32 v50, 16, v81
	v_and_b32_e32 v51, 0xffff0000, v81
	v_lshlrev_b32_e32 v52, 16, v82
	v_and_b32_e32 v53, 0xffff0000, v82
	v_exp_f32_e32 v2, v2
	v_exp_f32_e32 v3, v3
	v_mul_f32_e32 v50, 0xbfb8aa3b, v50
	v_mul_f32_e32 v51, 0xbfb8aa3b, v51
	v_mul_f32_e32 v52, 0xbfb8aa3b, v52
	v_mul_f32_e32 v53, 0xbfb8aa3b, v53
	v_exp_f32_e32 v50, v50
	v_exp_f32_e32 v51, v51
	v_exp_f32_e32 v52, v52
	v_exp_f32_e32 v53, v53
	v_lshlrev_b32_e32 v54, 16, v83
	v_and_b32_e32 v55, 0xffff0000, v83
	v_rcp_f32_e32 v0, v0
	v_rcp_f32_e32 v1, v1
	v_add_f32_e32 v2, 1.0, v2
	v_add_f32_e32 v3, 1.0, v3
	v_mul_f32_e32 v54, 0xbfb8aa3b, v54
	v_mul_f32_e32 v55, 0xbfb8aa3b, v55
	v_rcp_f32_e32 v2, v2
	v_rcp_f32_e32 v3, v3
	v_rcp_f32_e32 v44, v44
	v_rcp_f32_e32 v45, v45
	v_add_f32_e32 v50, 1.0, v50
	v_add_f32_e32 v51, 1.0, v51
	v_add_f32_e32 v52, 1.0, v52
	v_add_f32_e32 v53, 1.0, v53
	v_exp_f32_e32 v54, v54
	v_exp_f32_e32 v55, v55
	v_rcp_f32_e32 v50, v50
	v_rcp_f32_e32 v51, v51
	v_rcp_f32_e32 v52, v52
	v_rcp_f32_e32 v53, v53
	v_pk_mul_f32 v[0:1], v[0:1], v[40:41]
	v_pk_mul_f32 v[2:3], v[2:3], v[42:43]
	v_add_f32_e32 v40, v0, v1
	v_add_f32_e32 v54, 1.0, v54
	v_add_f32_e32 v55, 1.0, v55
	v_pk_mul_f32 v[82:83], v[44:45], v[36:37]
	v_add_f32_e32 v40, v2, v40
	v_rcp_f32_e32 v54, v54
	v_rcp_f32_e32 v55, v55
	v_pk_mul_f32 v[80:81], v[50:51], v[38:39]
	v_pk_mul_f32 v[74:75], v[52:53], v[32:33]
	v_add_f32_e32 v32, v82, v83
	v_add_f32_e32 v40, v3, v40
	v_add_f32_e32 v32, v80, v32
	v_add_f32_e32 v40, v84, v40
	v_add_f32_e32 v32, v81, v32
	v_add_f32_e32 v40, v85, v40
	v_add_f32_e32 v32, v74, v32
	v_add_f32_e32 v40, v76, v40
	v_pk_mul_f32 v[72:73], v[54:55], v[34:35]
	v_add_f32_e32 v32, v75, v32
	v_add_f32_e32 v40, v77, v40
	v_add_f32_e32 v32, v72, v32
	v_add_f32_e32 v56, 0, v40
	v_add_f32_e32 v32, v73, v32
	v_pk_mul_f32 v[40:41], v[0:1], v[0:1]
	v_add_f32_e32 v44, v32, v56
	v_pk_mul_f32 v[32:33], v[82:83], v[82:83]
	v_pk_mul_f32 v[42:43], v[2:3], v[2:3]
	v_pk_mul_f32 v[34:35], v[80:81], v[80:81]
	v_add_f32_e32 v32, v32, v33
	v_add_f32_e32 v33, v40, v41
	v_add_f32_e32 v32, v34, v32
	v_add_f32_e32 v33, v42, v33
	v_pk_mul_f32 v[46:47], v[84:85], v[84:85]
	v_pk_mul_f32 v[36:37], v[74:75], v[74:75]
	v_add_f32_e32 v32, v35, v32
	v_add_f32_e32 v33, v43, v33
	v_add_f32_e32 v32, v36, v32
	v_add_f32_e32 v33, v46, v33
	v_pk_mul_f32 v[48:49], v[76:77], v[76:77]
	v_pk_mul_f32 v[38:39], v[72:73], v[72:73]
	v_add_f32_e32 v32, v37, v32
	v_add_f32_e32 v33, v47, v33
	v_add_f32_e32 v32, v38, v32
	v_add_f32_e32 v33, v48, v33
	v_add_f32_e32 v32, v39, v32
	v_add_f32_e32 v33, v49, v33
	v_add_f32_e32 v35, v33, v32
	ds_bpermute_b32 v34, v172, v44
	ds_bpermute_b32 v36, v172, v35
	s_lshl_b64 s[0:1], s[20:21], 10
	s_waitcnt lgkmcnt(1)
	v_add_f32_e32 v32, v44, v34
	s_waitcnt lgkmcnt(0)
	v_add_f32_e32 v34, v35, v36
	ds_bpermute_b32 v33, v173, v32
	ds_bpermute_b32 v35, v173, v34
	s_and_saveexec_b64 s[20:21], vcc
	s_cbranch_execz .LBB0_614
	s_waitcnt lgkmcnt(1)
	v_add_f32_e32 v32, v32, v33
	s_waitcnt lgkmcnt(0)
	v_add_f32_e32 v33, v34, v35
	v_add_u32_e32 v34, 0xc0, v177
	ds_write2st64_b32 v34, v32, v33 offset0:2 offset1:18
	s_branch .LBB0_614
	s_nop 0
	s_nop 0
	s_nop 0
	s_nop 0
	s_nop 0
	s_nop 0
	s_nop 0
	s_nop 0
	s_nop 0
	s_nop 0
	s_nop 0
	s_nop 0
	s_nop 0
	s_nop 0
	s_nop 0
	s_nop 0
	s_nop 0
	s_nop 0
	s_nop 0
	s_nop 0
	s_nop 0
	s_nop 0
	s_nop 0
	s_nop 0
	s_nop 0
	s_nop 0
	s_nop 0
	s_nop 0
	s_nop 0
	s_nop 0
	s_nop 0
	s_nop 0
	s_nop 0
	s_nop 0
	s_nop 0
	s_nop 0
	s_nop 0
	s_nop 0
